# v31 + ping-pong GEMM K loops: the leading wave half enters the pre-MFMA barrier with its last four (second-group) operand reads in flight, waits for them before the 17th MFMA; reads reordered B0, A, B
# speedup vs baseline: 1.0034x; 1.0034x over previous
; #define PG8_STAGE(bufoff, gbase, voff) do { _Pragma("unroll") for (int _i = 0; _i < 2; ++_i) \
;         __builtin_amdgcn_global_load_lds((const unsigned*)((const char*)(gbase) + (voff)[_i]), (LAS unsigned*)(lds + (bufoff) + ldsw + _i * 8192), 16, 0, 0); } while (0)
; #define PG8_LDA(dst, b, h) do { _Pragma("unroll") for (int m = 0; m < 4; ++m) _Pragma("unroll") for (int k = 0; k < 2; ++k) dst[m][k] = *(const LAS bf16x8*)(lds + PG8_SA(b, h) + aoff + m * 2048 + k * 1024); } while (0)
; #define PG8_LDB(dst, b, h) do { _Pragma("unroll") for (int n = 0; n < 2; ++n) _Pragma("unroll") for (int k = 0; k < 2; ++k) dst[n][k] = *(const LAS bf16x8*)(lds + PG8_SB(b, h) + boff + n * 2048 + k * 1024); } while (0)
; #define PG8_MMA(ai, bj, At, Bt) do { __builtin_amdgcn_s_setprio(1); _Pragma("unroll") for (int m = 0; m < 4; ++m) _Pragma("unroll") for (int n = 0; n < 2; ++n) _Pragma("unroll") for (int k = 0; k < 2; ++k) \
;         acc[ai][bj][m][n] = __builtin_amdgcn_mfma_f32_16x16x32_bf16(Bt[n][k], At[m][k], acc[ai][bj][m][n], 0, 0, 0); __builtin_amdgcn_s_setprio(0); } while (0)
; #define PG8_WAIT_V(n) asm volatile("s_waitcnt vmcnt(" #n ")" ::: "memory")
; #define PG8_WAIT_L(n) asm volatile("s_waitcnt lgkmcnt(" #n ")" ::: "memory")
; #define PG8_BAR __builtin_amdgcn_s_barrier()
; #define PG8_SCHED __builtin_amdgcn_sched_barrier(0)
; template <class Epi>
; __device__ __forceinline__ void gemm_phase(LAS unsigned char* lds, const Gemm g, const StaticOrder& S, const Epi& E, int wave_s) {
;     ...
;             PG8_LDB(B0, 0, 0); PG8_LDB(B1, 0, 1); PG8_SCHED; PG8_LDA(At, 0, 0); PG8_STAGE(PG8_SA(1, 1), a1 + hstepA, voffA);
;             PG8_WAIT_V(8); PG8_WAIT_L(0); PG8_BAR; PG8_MMA(0, 0, At, B0); PG8_MMA(0, 1, At, B1); PG8_BAR; PG8_SCHED;
;             PG8_LDA(At, 0, 1); PG8_STAGE(PG8_SB(0, 0), b2, voffB); PG8_STAGE(PG8_SB(0, 1), b2 + hstepB, voffB); PG8_STAGE(PG8_SA(0, 0), a2, voffA);
;             PG8_WAIT_V(8); PG8_WAIT_L(0); PG8_BAR; PG8_MMA(1, 0, At, B0); PG8_MMA(1, 1, At, B1); PG8_BAR; PG8_SCHED;
.LBB0_215:
	s_add_u32 s26, s4, 0xfffc0080
	s_addc_u32 s27, s5, -1
	s_add_i32 s49, 0, 0x10000
	s_cmp_eq_u32 s48, 12
	s_cselect_b32 s31, s13, s27
	s_cselect_b32 s30, s44, s26
	v_add_u32_e32 v12, s49, v148
	s_cselect_b32 s27, s11, s47
	s_cselect_b32 s26, s45, s46
	s_add_i32 s52, 0, 0x14000
	ds_read_b128 v[150:153], v12
	ds_read_b128 v[154:157], v12 offset:1024
	ds_read_b128 v[158:161], v12 offset:2048
	ds_read_b128 v[162:165], v12 offset:3072
	v_add_u32_e32 v12, s52, v148
	ds_read_b128 v[190:193], v149
	ds_read_b128 v[194:197], v149 offset:1024
	ds_read_b128 v[198:201], v149 offset:2048
	ds_read_b128 v[202:205], v149 offset:3072
	ds_read_b128 v[206:209], v149 offset:4096
	ds_read_b128 v[210:213], v149 offset:5120
	ds_read_b128 v[214:217], v149 offset:6144
	ds_read_b128 v[218:221], v149 offset:7168
	ds_read_b128 v[166:169], v12
	ds_read_b128 v[178:181], v12 offset:1024
	ds_read_b128 v[182:185], v12 offset:2048
	ds_read_b128 v[186:189], v12 offset:3072
	v_lshl_add_u64 v[170:171], s[4:5], 0, v[144:145]
	s_add_i32 m0, s20, 0xc000
	global_load_lds_dwordx4 v[170:171], off
	v_lshl_add_u64 v[170:171], s[4:5], 0, v[146:147]
	s_add_i32 m0, s20, 0xe000
	s_nop 0
	global_load_lds_dwordx4 v[170:171], off
	s_waitcnt vmcnt(8)
	s_cmp_lg_u64 s[8:9], 0
	s_cbranch_scc1 .Lpp_lead_1
	s_waitcnt lgkmcnt(0)
.Lpp_lead_1:
	s_waitcnt lgkmcnt(4)
	s_barrier
	s_setprio 1
	s_waitcnt lgkmcnt(4)
	v_mfma_f32_16x16x32_bf16 v[126:129], v[150:153], v[190:193], v[126:129]
	v_mfma_f32_16x16x32_bf16 v[122:125], v[158:161], v[190:193], v[122:125]
	v_mfma_f32_16x16x32_bf16 v[118:121], v[150:153], v[198:201], v[118:121]
	v_mfma_f32_16x16x32_bf16 v[114:117], v[158:161], v[198:201], v[114:117]
	v_mfma_f32_16x16x32_bf16 v[110:113], v[150:153], v[206:209], v[110:113]
	v_mfma_f32_16x16x32_bf16 v[106:109], v[158:161], v[206:209], v[106:109]
	v_mfma_f32_16x16x32_bf16 v[102:105], v[150:153], v[214:217], v[102:105]
	v_mfma_f32_16x16x32_bf16 v[98:101], v[158:161], v[214:217], v[98:101]
	v_mfma_f32_16x16x32_bf16 v[126:129], v[154:157], v[194:197], v[126:129]
	v_mfma_f32_16x16x32_bf16 v[122:125], v[162:165], v[194:197], v[122:125]
	v_mfma_f32_16x16x32_bf16 v[118:121], v[154:157], v[202:205], v[118:121]
	v_mfma_f32_16x16x32_bf16 v[114:117], v[162:165], v[202:205], v[114:117]
	v_mfma_f32_16x16x32_bf16 v[110:113], v[154:157], v[210:213], v[110:113]
	v_mfma_f32_16x16x32_bf16 v[106:109], v[162:165], v[210:213], v[106:109]
	v_mfma_f32_16x16x32_bf16 v[102:105], v[154:157], v[218:221], v[102:105]
	v_mfma_f32_16x16x32_bf16 v[98:101], v[162:165], v[218:221], v[98:101]
	s_setprio 0
	s_setprio 1
	s_waitcnt lgkmcnt(0)
	v_mfma_f32_16x16x32_bf16 v[62:65], v[166:169], v[190:193], v[62:65]
	v_mfma_f32_16x16x32_bf16 v[58:61], v[182:185], v[190:193], v[58:61]
	v_mfma_f32_16x16x32_bf16 v[54:57], v[166:169], v[198:201], v[54:57]
	v_mfma_f32_16x16x32_bf16 v[50:53], v[182:185], v[198:201], v[50:53]
	v_mfma_f32_16x16x32_bf16 v[46:49], v[166:169], v[206:209], v[46:49]
	v_mfma_f32_16x16x32_bf16 v[42:45], v[182:185], v[206:209], v[42:45]
	v_mfma_f32_16x16x32_bf16 v[38:41], v[166:169], v[214:217], v[38:41]
	v_mfma_f32_16x16x32_bf16 v[34:37], v[182:185], v[214:217], v[34:37]
	v_mfma_f32_16x16x32_bf16 v[62:65], v[178:181], v[194:197], v[62:65]
	v_mfma_f32_16x16x32_bf16 v[58:61], v[186:189], v[194:197], v[58:61]
	v_mfma_f32_16x16x32_bf16 v[54:57], v[178:181], v[202:205], v[54:57]
	v_mfma_f32_16x16x32_bf16 v[50:53], v[186:189], v[202:205], v[50:53]
	v_mfma_f32_16x16x32_bf16 v[46:49], v[178:181], v[210:213], v[46:49]
	v_mfma_f32_16x16x32_bf16 v[42:45], v[186:189], v[210:213], v[42:45]
	v_mfma_f32_16x16x32_bf16 v[38:41], v[178:181], v[218:221], v[38:41]
	v_mfma_f32_16x16x32_bf16 v[34:37], v[186:189], v[218:221], v[34:37]
	s_setprio 0
	s_barrier
	s_add_i32 s49, s49, s18
	v_lshl_add_u64 v[170:171], s[26:27], 0, v[134:135]
	s_mov_b32 m0, s49
	ds_read_b128 v[190:193], v149 offset:16384
	ds_read_b128 v[194:197], v149 offset:17408
	ds_read_b128 v[198:201], v149 offset:18432
	ds_read_b128 v[202:205], v149 offset:19456
	ds_read_b128 v[206:209], v149 offset:20480
	ds_read_b128 v[210:213], v149 offset:21504
	ds_read_b128 v[214:217], v149 offset:22528
	ds_read_b128 v[218:221], v149 offset:23552
	global_load_lds_dwordx4 v[170:171], off
	s_add_i32 m0, s49, 0x2000
	s_add_u32 s50, s26, 0x40000
	v_lshl_add_u64 v[172:173], s[26:27], 0, v[130:131]
	s_addc_u32 s51, s27, 0
	s_add_i32 s49, s52, s18
	global_load_lds_dwordx4 v[172:173], off
	v_lshl_add_u64 v[174:175], s[50:51], 0, v[134:135]
	s_mov_b32 m0, s49
	v_lshl_add_u64 v[176:177], s[30:31], 0, v[132:133]
	global_load_lds_dwordx4 v[174:175], off
	v_lshl_add_u64 v[174:175], s[50:51], 0, v[130:131]
	s_add_i32 m0, s49, 0x2000
	s_nop 0
	global_load_lds_dwordx4 v[174:175], off
	v_lshl_add_u64 v[174:175], s[30:31], 0, v[136:137]
	s_mov_b32 m0, s20
	s_nop 0
	global_load_lds_dwordx4 v[174:175], off
	s_mov_b32 m0, s25
	s_nop 0
	global_load_lds_dwordx4 v[176:177], off
	s_waitcnt vmcnt(8)
	s_waitcnt lgkmcnt(0)
	s_barrier
; #define PG8_STAGE(bufoff, gbase, voff) do { _Pragma("unroll") for (int _i = 0; _i < 2; ++_i) \
;         __builtin_amdgcn_global_load_lds((const unsigned*)((const char*)(gbase) + (voff)[_i]), (LAS unsigned*)(lds + (bufoff) + ldsw + _i * 8192), 16, 0, 0); } while (0)
; #define PG8_LDA(dst, b, h) do { _Pragma("unroll") for (int m = 0; m < 4; ++m) _Pragma("unroll") for (int k = 0; k < 2; ++k) dst[m][k] = *(const LAS bf16x8*)(lds + PG8_SA(b, h) + aoff + m * 2048 + k * 1024); } while (0)
; #define PG8_LDB(dst, b, h) do { _Pragma("unroll") for (int n = 0; n < 2; ++n) _Pragma("unroll") for (int k = 0; k < 2; ++k) dst[n][k] = *(const LAS bf16x8*)(lds + PG8_SB(b, h) + boff + n * 2048 + k * 1024); } while (0)
; #define PG8_MMA(ai, bj, At, Bt) do { __builtin_amdgcn_s_setprio(1); _Pragma("unroll") for (int m = 0; m < 4; ++m) _Pragma("unroll") for (int n = 0; n < 2; ++n) _Pragma("unroll") for (int k = 0; k < 2; ++k) \
;         acc[ai][bj][m][n] = __builtin_amdgcn_mfma_f32_16x16x32_bf16(Bt[n][k], At[m][k], acc[ai][bj][m][n], 0, 0, 0); __builtin_amdgcn_s_setprio(0); } while (0)
; #define PG8_WAIT_V(n) asm volatile("s_waitcnt vmcnt(" #n ")" ::: "memory")
; #define PG8_WAIT_L(n) asm volatile("s_waitcnt lgkmcnt(" #n ")" ::: "memory")
; #define PG8_BAR __builtin_amdgcn_s_barrier()
; #define PG8_SCHED __builtin_amdgcn_sched_barrier(0)
; template <class Epi>
; __device__ __forceinline__ void gemm_phase(LAS unsigned char* lds, const Gemm g, const StaticOrder& S, const Epi& E, int wave_s) {
;     ...
;             PG8_WAIT_V(8); PG8_WAIT_L(0); PG8_BAR; PG8_MMA(1, 0, At, B0); PG8_MMA(1, 1, At, B1); PG8_BAR; PG8_SCHED;
;             PG8_LDB(B0, 1, 0); PG8_LDB(B1, 1, 1); PG8_SCHED; PG8_LDA(At, 1, 0); PG8_STAGE(PG8_SA(0, 1), a2 + hstepA, voffA);
;             PG8_WAIT_V(8); PG8_WAIT_L(0); PG8_BAR; PG8_MMA(0, 0, At, B0); PG8_MMA(0, 1, At, B1); PG8_BAR; PG8_SCHED;
	s_setprio 1
	s_waitcnt lgkmcnt(0)
	v_mfma_f32_16x16x32_bf16 v[94:97], v[150:153], v[190:193], v[94:97]
	v_mfma_f32_16x16x32_bf16 v[90:93], v[158:161], v[190:193], v[90:93]
	v_mfma_f32_16x16x32_bf16 v[86:89], v[150:153], v[198:201], v[86:89]
	v_mfma_f32_16x16x32_bf16 v[82:85], v[158:161], v[198:201], v[82:85]
	v_mfma_f32_16x16x32_bf16 v[78:81], v[150:153], v[206:209], v[78:81]
	v_mfma_f32_16x16x32_bf16 v[74:77], v[158:161], v[206:209], v[74:77]
	v_mfma_f32_16x16x32_bf16 v[70:73], v[150:153], v[214:217], v[70:73]
	v_mfma_f32_16x16x32_bf16 v[66:69], v[158:161], v[214:217], v[66:69]
	v_mfma_f32_16x16x32_bf16 v[94:97], v[154:157], v[194:197], v[94:97]
	v_mfma_f32_16x16x32_bf16 v[90:93], v[162:165], v[194:197], v[90:93]
	v_mfma_f32_16x16x32_bf16 v[86:89], v[154:157], v[202:205], v[86:89]
	v_mfma_f32_16x16x32_bf16 v[82:85], v[162:165], v[202:205], v[82:85]
	v_mfma_f32_16x16x32_bf16 v[78:81], v[154:157], v[210:213], v[78:81]
	v_mfma_f32_16x16x32_bf16 v[74:77], v[162:165], v[210:213], v[74:77]
	v_mfma_f32_16x16x32_bf16 v[70:73], v[154:157], v[218:221], v[70:73]
	v_mfma_f32_16x16x32_bf16 v[66:69], v[162:165], v[218:221], v[66:69]
	s_setprio 0
	s_setprio 1
	v_mfma_f32_16x16x32_bf16 v[30:33], v[166:169], v[190:193], v[30:33]
	v_mfma_f32_16x16x32_bf16 v[26:29], v[182:185], v[190:193], v[26:29]
	v_mfma_f32_16x16x32_bf16 v[22:25], v[166:169], v[198:201], v[22:25]
	v_mfma_f32_16x16x32_bf16 v[18:21], v[182:185], v[198:201], v[18:21]
	v_mfma_f32_16x16x32_bf16 v[14:17], v[166:169], v[206:209], v[14:17]
	v_mfma_f32_16x16x32_bf16 v[8:11], v[182:185], v[206:209], v[8:11]
	v_mfma_f32_16x16x32_bf16 v[4:7], v[166:169], v[214:217], v[4:7]
	v_mfma_f32_16x16x32_bf16 v[0:3], v[182:185], v[214:217], v[0:3]
	v_mfma_f32_16x16x32_bf16 v[30:33], v[178:181], v[194:197], v[30:33]
	v_mfma_f32_16x16x32_bf16 v[26:29], v[186:189], v[194:197], v[26:29]
	v_mfma_f32_16x16x32_bf16 v[22:25], v[178:181], v[202:205], v[22:25]
	v_mfma_f32_16x16x32_bf16 v[18:21], v[186:189], v[202:205], v[18:21]
	v_mfma_f32_16x16x32_bf16 v[14:17], v[178:181], v[210:213], v[14:17]
	v_mfma_f32_16x16x32_bf16 v[8:11], v[186:189], v[210:213], v[8:11]
	v_mfma_f32_16x16x32_bf16 v[4:7], v[178:181], v[218:221], v[4:7]
	v_mfma_f32_16x16x32_bf16 v[0:3], v[186:189], v[218:221], v[0:3]
	s_setprio 0
	s_barrier
	s_add_i32 s49, 0, 0x18000
	v_add_u32_e32 v12, s49, v148
	s_add_i32 s50, 0, 0x1c000
	ds_read_b128 v[150:153], v12
	ds_read_b128 v[154:157], v12 offset:1024
	ds_read_b128 v[158:161], v12 offset:2048
	ds_read_b128 v[162:165], v12 offset:3072
	v_add_u32_e32 v12, s50, v148
	ds_read_b128 v[190:193], v149 offset:32768
	ds_read_b128 v[194:197], v149 offset:33792
	ds_read_b128 v[198:201], v149 offset:34816
	ds_read_b128 v[202:205], v149 offset:35840
	ds_read_b128 v[206:209], v149 offset:36864
	ds_read_b128 v[210:213], v149 offset:37888
	ds_read_b128 v[214:217], v149 offset:38912
	ds_read_b128 v[218:221], v149 offset:39936
	ds_read_b128 v[166:169], v12
	ds_read_b128 v[178:181], v12 offset:1024
	ds_read_b128 v[182:185], v12 offset:2048
	ds_read_b128 v[186:189], v12 offset:3072
	s_add_u32 s30, s30, 0x40000
	s_addc_u32 s31, s31, 0
	s_mov_b32 m0, s29
	v_lshl_add_u64 v[222:223], s[30:31], 0, v[136:137]
	global_load_lds_dwordx4 v[222:223], off
	v_lshl_add_u64 v[222:223], s[30:31], 0, v[132:133]
	s_mov_b32 m0, s35
	s_nop 0
	global_load_lds_dwordx4 v[222:223], off
	s_waitcnt vmcnt(8)
	s_cmp_lg_u64 s[8:9], 0
	s_cbranch_scc1 .Lpp_lead_2
	s_waitcnt lgkmcnt(0)
; #define PG8_STAGE(bufoff, gbase, voff) do { _Pragma("unroll") for (int _i = 0; _i < 2; ++_i) \
;         __builtin_amdgcn_global_load_lds((const unsigned*)((const char*)(gbase) + (voff)[_i]), (LAS unsigned*)(lds + (bufoff) + ldsw + _i * 8192), 16, 0, 0); } while (0)
; #define PG8_LDA(dst, b, h) do { _Pragma("unroll") for (int m = 0; m < 4; ++m) _Pragma("unroll") for (int k = 0; k < 2; ++k) dst[m][k] = *(const LAS bf16x8*)(lds + PG8_SA(b, h) + aoff + m * 2048 + k * 1024); } while (0)
; #define PG8_LDB(dst, b, h) do { _Pragma("unroll") for (int n = 0; n < 2; ++n) _Pragma("unroll") for (int k = 0; k < 2; ++k) dst[n][k] = *(const LAS bf16x8*)(lds + PG8_SB(b, h) + boff + n * 2048 + k * 1024); } while (0)
; #define PG8_MMA(ai, bj, At, Bt) do { __builtin_amdgcn_s_setprio(1); _Pragma("unroll") for (int m = 0; m < 4; ++m) _Pragma("unroll") for (int n = 0; n < 2; ++n) _Pragma("unroll") for (int k = 0; k < 2; ++k) \
;         acc[ai][bj][m][n] = __builtin_amdgcn_mfma_f32_16x16x32_bf16(Bt[n][k], At[m][k], acc[ai][bj][m][n], 0, 0, 0); __builtin_amdgcn_s_setprio(0); } while (0)
; #define PG8_WAIT_V(n) asm volatile("s_waitcnt vmcnt(" #n ")" ::: "memory")
; #define PG8_WAIT_L(n) asm volatile("s_waitcnt lgkmcnt(" #n ")" ::: "memory")
; #define PG8_BAR __builtin_amdgcn_s_barrier()
; #define PG8_SCHED __builtin_amdgcn_sched_barrier(0)
; template <class Epi>
; __device__ __forceinline__ void gemm_phase(LAS unsigned char* lds, const Gemm g, const StaticOrder& S, const Epi& E, int wave_s) {
;     ...
;             PG8_LDB(B0, 1, 0); PG8_LDB(B1, 1, 1); PG8_SCHED; PG8_LDA(At, 1, 0); PG8_STAGE(PG8_SA(0, 1), a2 + hstepA, voffA);
;             PG8_WAIT_V(8); PG8_WAIT_L(0); PG8_BAR; PG8_MMA(0, 0, At, B0); PG8_MMA(0, 1, At, B1); PG8_BAR; PG8_SCHED;
;             PG8_LDA(At, 1, 1); PG8_STAGE(PG8_SB(1, 0), b3, voffB); PG8_STAGE(PG8_SB(1, 1), b3 + hstepB, voffB); PG8_STAGE(PG8_SA(1, 0), a3, voffA);
;             PG8_WAIT_V(8); PG8_WAIT_L(0); PG8_BAR; PG8_MMA(1, 0, At, B0); PG8_MMA(1, 1, At, B1); PG8_BAR; PG8_SCHED;
;         }
.Lpp_lead_2:
	s_waitcnt lgkmcnt(4)
	s_barrier
	s_setprio 1
	s_waitcnt lgkmcnt(4)
	v_mfma_f32_16x16x32_bf16 v[126:129], v[150:153], v[190:193], v[126:129]
	v_mfma_f32_16x16x32_bf16 v[122:125], v[158:161], v[190:193], v[122:125]
	v_mfma_f32_16x16x32_bf16 v[118:121], v[150:153], v[198:201], v[118:121]
	v_mfma_f32_16x16x32_bf16 v[114:117], v[158:161], v[198:201], v[114:117]
	v_mfma_f32_16x16x32_bf16 v[110:113], v[150:153], v[206:209], v[110:113]
	v_mfma_f32_16x16x32_bf16 v[106:109], v[158:161], v[206:209], v[106:109]
	v_mfma_f32_16x16x32_bf16 v[102:105], v[150:153], v[214:217], v[102:105]
	v_mfma_f32_16x16x32_bf16 v[98:101], v[158:161], v[214:217], v[98:101]
	v_mfma_f32_16x16x32_bf16 v[126:129], v[154:157], v[194:197], v[126:129]
	v_mfma_f32_16x16x32_bf16 v[122:125], v[162:165], v[194:197], v[122:125]
	v_mfma_f32_16x16x32_bf16 v[118:121], v[154:157], v[202:205], v[118:121]
	v_mfma_f32_16x16x32_bf16 v[114:117], v[162:165], v[202:205], v[114:117]
	v_mfma_f32_16x16x32_bf16 v[110:113], v[154:157], v[210:213], v[110:113]
	v_mfma_f32_16x16x32_bf16 v[106:109], v[162:165], v[210:213], v[106:109]
	v_mfma_f32_16x16x32_bf16 v[102:105], v[154:157], v[218:221], v[102:105]
	v_mfma_f32_16x16x32_bf16 v[98:101], v[162:165], v[218:221], v[98:101]
	s_setprio 0
	s_setprio 1
	s_waitcnt lgkmcnt(0)
	v_mfma_f32_16x16x32_bf16 v[62:65], v[166:169], v[190:193], v[62:65]
	v_mfma_f32_16x16x32_bf16 v[58:61], v[182:185], v[190:193], v[58:61]
	v_mfma_f32_16x16x32_bf16 v[54:57], v[166:169], v[198:201], v[54:57]
	v_mfma_f32_16x16x32_bf16 v[50:53], v[182:185], v[198:201], v[50:53]
	v_mfma_f32_16x16x32_bf16 v[46:49], v[166:169], v[206:209], v[46:49]
	v_mfma_f32_16x16x32_bf16 v[42:45], v[182:185], v[206:209], v[42:45]
	v_mfma_f32_16x16x32_bf16 v[38:41], v[166:169], v[214:217], v[38:41]
	v_mfma_f32_16x16x32_bf16 v[34:37], v[182:185], v[214:217], v[34:37]
	v_mfma_f32_16x16x32_bf16 v[62:65], v[178:181], v[194:197], v[62:65]
	v_mfma_f32_16x16x32_bf16 v[58:61], v[186:189], v[194:197], v[58:61]
	v_mfma_f32_16x16x32_bf16 v[54:57], v[178:181], v[202:205], v[54:57]
	v_mfma_f32_16x16x32_bf16 v[50:53], v[186:189], v[202:205], v[50:53]
	v_mfma_f32_16x16x32_bf16 v[46:49], v[178:181], v[210:213], v[46:49]
	v_mfma_f32_16x16x32_bf16 v[42:45], v[186:189], v[210:213], v[42:45]
	v_mfma_f32_16x16x32_bf16 v[38:41], v[178:181], v[218:221], v[38:41]
	v_mfma_f32_16x16x32_bf16 v[34:37], v[186:189], v[218:221], v[34:37]
	s_setprio 0
	s_barrier
	s_add_i32 s30, s49, s18
	v_lshl_add_u64 v[170:171], v[170:171], 0, s[84:85]
	s_mov_b32 m0, s30
	ds_read_b128 v[190:193], v149 offset:49152
	ds_read_b128 v[194:197], v149 offset:50176
	ds_read_b128 v[198:201], v149 offset:51200
	ds_read_b128 v[202:205], v149 offset:52224
	ds_read_b128 v[206:209], v149 offset:53248
	ds_read_b128 v[210:213], v149 offset:54272
	ds_read_b128 v[214:217], v149 offset:55296
	ds_read_b128 v[218:221], v149 offset:56320
	global_load_lds_dwordx4 v[170:171], off
	s_add_i32 m0, s30, 0x2000
	s_add_u32 s26, s26, 0x40080
	v_lshl_add_u64 v[170:171], v[172:173], 0, s[84:85]
	s_addc_u32 s27, s27, 0
	s_add_i32 s30, s50, s18
	global_load_lds_dwordx4 v[170:171], off
	v_lshl_add_u64 v[170:171], s[26:27], 0, v[134:135]
	s_mov_b32 m0, s30
	s_nop 0
	global_load_lds_dwordx4 v[170:171], off
	v_lshl_add_u64 v[170:171], s[26:27], 0, v[130:131]
	s_add_i32 m0, s30, 0x2000
	s_nop 0
	global_load_lds_dwordx4 v[170:171], off
	v_lshl_add_u64 v[170:171], v[174:175], 0, s[84:85]
	s_mov_b32 m0, s37
	s_nop 0
	global_load_lds_dwordx4 v[170:171], off
	v_lshl_add_u64 v[170:171], v[176:177], 0, s[84:85]
	s_mov_b32 m0, s40
	s_nop 0
	global_load_lds_dwordx4 v[170:171], off
	s_waitcnt vmcnt(8)
	s_waitcnt lgkmcnt(0)
	s_barrier
	s_setprio 1
	s_waitcnt lgkmcnt(0)
	v_mfma_f32_16x16x32_bf16 v[94:97], v[150:153], v[190:193], v[94:97]
	v_mfma_f32_16x16x32_bf16 v[90:93], v[158:161], v[190:193], v[90:93]
	v_mfma_f32_16x16x32_bf16 v[86:89], v[150:153], v[198:201], v[86:89]
	v_mfma_f32_16x16x32_bf16 v[82:85], v[158:161], v[198:201], v[82:85]
	v_mfma_f32_16x16x32_bf16 v[78:81], v[150:153], v[206:209], v[78:81]
	v_mfma_f32_16x16x32_bf16 v[74:77], v[158:161], v[206:209], v[74:77]
	v_mfma_f32_16x16x32_bf16 v[70:73], v[150:153], v[214:217], v[70:73]
	v_mfma_f32_16x16x32_bf16 v[66:69], v[158:161], v[214:217], v[66:69]
	v_mfma_f32_16x16x32_bf16 v[94:97], v[154:157], v[194:197], v[94:97]
	v_mfma_f32_16x16x32_bf16 v[90:93], v[162:165], v[194:197], v[90:93]
	v_mfma_f32_16x16x32_bf16 v[86:89], v[154:157], v[202:205], v[86:89]
	v_mfma_f32_16x16x32_bf16 v[82:85], v[162:165], v[202:205], v[82:85]
	v_mfma_f32_16x16x32_bf16 v[78:81], v[154:157], v[210:213], v[78:81]
	v_mfma_f32_16x16x32_bf16 v[74:77], v[162:165], v[210:213], v[74:77]
	v_mfma_f32_16x16x32_bf16 v[70:73], v[154:157], v[218:221], v[70:73]
	v_mfma_f32_16x16x32_bf16 v[66:69], v[162:165], v[218:221], v[66:69]
	s_setprio 0
	s_setprio 1
	v_mfma_f32_16x16x32_bf16 v[30:33], v[166:169], v[190:193], v[30:33]
	v_mfma_f32_16x16x32_bf16 v[26:29], v[182:185], v[190:193], v[26:29]
	v_mfma_f32_16x16x32_bf16 v[22:25], v[166:169], v[198:201], v[22:25]
	v_mfma_f32_16x16x32_bf16 v[18:21], v[182:185], v[198:201], v[18:21]
	v_mfma_f32_16x16x32_bf16 v[14:17], v[166:169], v[206:209], v[14:17]
	v_mfma_f32_16x16x32_bf16 v[8:11], v[182:185], v[206:209], v[8:11]
	v_mfma_f32_16x16x32_bf16 v[4:7], v[166:169], v[214:217], v[4:7]
	v_mfma_f32_16x16x32_bf16 v[0:3], v[182:185], v[214:217], v[0:3]
	v_mfma_f32_16x16x32_bf16 v[30:33], v[178:181], v[194:197], v[30:33]
	v_mfma_f32_16x16x32_bf16 v[26:29], v[186:189], v[194:197], v[26:29]
	v_mfma_f32_16x16x32_bf16 v[22:25], v[178:181], v[202:205], v[22:25]
	v_mfma_f32_16x16x32_bf16 v[18:21], v[186:189], v[202:205], v[18:21]
	v_mfma_f32_16x16x32_bf16 v[14:17], v[178:181], v[210:213], v[14:17]
	v_mfma_f32_16x16x32_bf16 v[8:11], v[186:189], v[210:213], v[8:11]
	v_mfma_f32_16x16x32_bf16 v[4:7], v[178:181], v[218:221], v[4:7]
	v_mfma_f32_16x16x32_bf16 v[0:3], v[186:189], v[218:221], v[0:3]
	s_setprio 0
	s_barrier
	s_add_i32 s48, s48, 2
	s_add_u32 s4, s4, 0x100
	s_addc_u32 s5, s5, 0
	s_add_u32 s46, s46, 0x100
	s_addc_u32 s47, s47, 0
	s_cmp_gt_u32 s48, 13
	s_cbranch_scc0 .LBB0_215
	s_and_b64 vcc, exec, s[8:9]
	s_cbranch_vccz .LBB0_218
	s_barrier

; #define PG8_STAGE(bufoff, gbase, voff) do { _Pragma("unroll") for (int _i = 0; _i < 2; ++_i) \
;         __builtin_amdgcn_global_load_lds((const unsigned*)((const char*)(gbase) + (voff)[_i]), (LAS unsigned*)(lds + (bufoff) + ldsw + _i * 8192), 16, 0, 0); } while (0)
; #define PG8_LDA(dst, b, h) do { _Pragma("unroll") for (int m = 0; m < 4; ++m) _Pragma("unroll") for (int k = 0; k < 2; ++k) dst[m][k] = *(const LAS bf16x8*)(lds + PG8_SA(b, h) + aoff + m * 2048 + k * 1024); } while (0)
; #define PG8_LDB(dst, b, h) do { _Pragma("unroll") for (int n = 0; n < 2; ++n) _Pragma("unroll") for (int k = 0; k < 2; ++k) dst[n][k] = *(const LAS bf16x8*)(lds + PG8_SB(b, h) + boff + n * 2048 + k * 1024); } while (0)
; #define PG8_MMA(ai, bj, At, Bt) do { __builtin_amdgcn_s_setprio(1); _Pragma("unroll") for (int m = 0; m < 4; ++m) _Pragma("unroll") for (int n = 0; n < 2; ++n) _Pragma("unroll") for (int k = 0; k < 2; ++k) \
;         acc[ai][bj][m][n] = __builtin_amdgcn_mfma_f32_16x16x32_bf16(Bt[n][k], At[m][k], acc[ai][bj][m][n], 0, 0, 0); __builtin_amdgcn_s_setprio(0); } while (0)
; #define PG8_WAIT_V(n) asm volatile("s_waitcnt vmcnt(" #n ")" ::: "memory")
; #define PG8_WAIT_L(n) asm volatile("s_waitcnt lgkmcnt(" #n ")" ::: "memory")
; #define PG8_BAR __builtin_amdgcn_s_barrier()
; #define PG8_SCHED __builtin_amdgcn_sched_barrier(0)
; template <class Epi>
; __device__ __forceinline__ void gemm_phase(LAS unsigned char* lds, const Gemm g, const StaticOrder& S, const Epi& E, int wave_s) {
;     ...
;             PG8_LDB(B0, 0, 0); PG8_LDB(B1, 0, 1); PG8_SCHED; PG8_LDA(At, 0, 0); PG8_STAGE(PG8_SA(1, 1), a1 + hstepA, voffA);
;             PG8_WAIT_V(8); PG8_WAIT_L(0); PG8_BAR; PG8_MMA(0, 0, At, B0); PG8_MMA(0, 1, At, B1); PG8_BAR; PG8_SCHED;
;             PG8_LDA(At, 0, 1); PG8_STAGE(PG8_SB(0, 0), b2, voffB); PG8_STAGE(PG8_SB(0, 1), b2 + hstepB, voffB); PG8_STAGE(PG8_SA(0, 0), a2, voffA);
;             PG8_WAIT_V(8); PG8_WAIT_L(0); PG8_BAR; PG8_MMA(1, 0, At, B0); PG8_MMA(1, 1, At, B1); PG8_BAR; PG8_SCHED;
.LBB0_343:
	s_add_u32 s6, s22, 0x100
	s_addc_u32 s7, s23, 0
	s_add_i32 s51, 0, 0x10000
	s_cmp_eq_u32 s50, 2
	s_cselect_b32 s31, s13, s7
	s_cselect_b32 s30, s12, s6
	v_add_u32_e32 v12, s51, v166
	s_cselect_b32 s27, s17, s49
	s_cselect_b32 s26, s16, s48
	s_add_i32 s52, 0, 0x14000
	ds_read_b128 v[130:133], v12
	ds_read_b128 v[134:137], v12 offset:1024
	ds_read_b128 v[138:141], v12 offset:2048
	ds_read_b128 v[142:145], v12 offset:3072
	v_add_u32_e32 v12, s52, v166
	ds_read_b128 v[188:191], v167
	ds_read_b128 v[192:195], v167 offset:1024
	ds_read_b128 v[196:199], v167 offset:2048
	ds_read_b128 v[200:203], v167 offset:3072
	ds_read_b128 v[204:207], v167 offset:4096
	ds_read_b128 v[208:211], v167 offset:5120
	ds_read_b128 v[212:215], v167 offset:6144
	ds_read_b128 v[216:219], v167 offset:7168
	ds_read_b128 v[146:149], v12
	ds_read_b128 v[150:153], v12 offset:1024
	ds_read_b128 v[168:171], v12 offset:2048
	ds_read_b128 v[184:187], v12 offset:3072
	v_lshl_add_u64 v[172:173], s[22:23], 0, v[180:181]
	s_add_i32 m0, s29, 0xc000
	global_load_lds_dwordx4 v[172:173], off
	v_lshl_add_u64 v[172:173], s[22:23], 0, v[182:183]
	s_add_i32 m0, s29, 0xe000
	s_nop 0
	global_load_lds_dwordx4 v[172:173], off
	s_waitcnt vmcnt(8)
	s_cmp_lg_u64 s[10:11], 0
	s_cbranch_scc1 .Lpp_lead_3
	s_waitcnt lgkmcnt(0)
.Lpp_lead_3:
	s_waitcnt lgkmcnt(4)
	s_barrier
	s_setprio 1
	s_waitcnt lgkmcnt(4)
	v_mfma_f32_16x16x32_bf16 v[126:129], v[130:133], v[188:191], v[126:129]
	v_mfma_f32_16x16x32_bf16 v[122:125], v[138:141], v[188:191], v[122:125]
	v_mfma_f32_16x16x32_bf16 v[118:121], v[130:133], v[196:199], v[118:121]
	v_mfma_f32_16x16x32_bf16 v[114:117], v[138:141], v[196:199], v[114:117]
	v_mfma_f32_16x16x32_bf16 v[110:113], v[130:133], v[204:207], v[110:113]
	v_mfma_f32_16x16x32_bf16 v[106:109], v[138:141], v[204:207], v[106:109]
	v_mfma_f32_16x16x32_bf16 v[102:105], v[130:133], v[212:215], v[102:105]
	v_mfma_f32_16x16x32_bf16 v[98:101], v[138:141], v[212:215], v[98:101]
	v_mfma_f32_16x16x32_bf16 v[126:129], v[134:137], v[192:195], v[126:129]
	v_mfma_f32_16x16x32_bf16 v[122:125], v[142:145], v[192:195], v[122:125]
	v_mfma_f32_16x16x32_bf16 v[118:121], v[134:137], v[200:203], v[118:121]
	v_mfma_f32_16x16x32_bf16 v[114:117], v[142:145], v[200:203], v[114:117]
	v_mfma_f32_16x16x32_bf16 v[110:113], v[134:137], v[208:211], v[110:113]
	v_mfma_f32_16x16x32_bf16 v[106:109], v[142:145], v[208:211], v[106:109]
	v_mfma_f32_16x16x32_bf16 v[102:105], v[134:137], v[216:219], v[102:105]
	v_mfma_f32_16x16x32_bf16 v[98:101], v[142:145], v[216:219], v[98:101]
	s_setprio 0
	s_setprio 1
	s_waitcnt lgkmcnt(0)
	v_mfma_f32_16x16x32_bf16 v[62:65], v[146:149], v[188:191], v[62:65]
	v_mfma_f32_16x16x32_bf16 v[58:61], v[168:171], v[188:191], v[58:61]
	v_mfma_f32_16x16x32_bf16 v[54:57], v[146:149], v[196:199], v[54:57]
	v_mfma_f32_16x16x32_bf16 v[50:53], v[168:171], v[196:199], v[50:53]
	v_mfma_f32_16x16x32_bf16 v[46:49], v[146:149], v[204:207], v[46:49]
	v_mfma_f32_16x16x32_bf16 v[42:45], v[168:171], v[204:207], v[42:45]
	v_mfma_f32_16x16x32_bf16 v[38:41], v[146:149], v[212:215], v[38:41]
	v_mfma_f32_16x16x32_bf16 v[34:37], v[168:171], v[212:215], v[34:37]
	v_mfma_f32_16x16x32_bf16 v[62:65], v[150:153], v[192:195], v[62:65]
	v_mfma_f32_16x16x32_bf16 v[58:61], v[184:187], v[192:195], v[58:61]
	v_mfma_f32_16x16x32_bf16 v[54:57], v[150:153], v[200:203], v[54:57]
	v_mfma_f32_16x16x32_bf16 v[50:53], v[184:187], v[200:203], v[50:53]
	v_mfma_f32_16x16x32_bf16 v[46:49], v[150:153], v[208:211], v[46:49]
	v_mfma_f32_16x16x32_bf16 v[42:45], v[184:187], v[208:211], v[42:45]
	v_mfma_f32_16x16x32_bf16 v[38:41], v[150:153], v[216:219], v[38:41]
	v_mfma_f32_16x16x32_bf16 v[34:37], v[184:187], v[216:219], v[34:37]
	s_setprio 0
	s_barrier
	s_add_i32 s22, s51, s25
	v_lshl_add_u64 v[172:173], s[26:27], 0, v[158:159]
	s_mov_b32 m0, s22
	ds_read_b128 v[188:191], v167 offset:16384
	ds_read_b128 v[192:195], v167 offset:17408
	ds_read_b128 v[196:199], v167 offset:18432
	ds_read_b128 v[200:203], v167 offset:19456
	ds_read_b128 v[204:207], v167 offset:20480
	ds_read_b128 v[208:211], v167 offset:21504
	ds_read_b128 v[212:215], v167 offset:22528
	ds_read_b128 v[216:219], v167 offset:23552
	global_load_lds_dwordx4 v[172:173], off
	s_add_i32 m0, s22, 0x2000
	s_add_u32 s22, s26, 0x18000
	v_lshl_add_u64 v[174:175], s[26:27], 0, v[154:155]
	s_addc_u32 s23, s27, 0
	s_add_i32 s51, s52, s25
	global_load_lds_dwordx4 v[174:175], off
	v_lshl_add_u64 v[176:177], s[22:23], 0, v[158:159]
	s_mov_b32 m0, s51
	v_lshl_add_u64 v[220:221], s[30:31], 0, v[156:157]
	global_load_lds_dwordx4 v[176:177], off
	v_lshl_add_u64 v[176:177], s[22:23], 0, v[154:155]
	s_add_i32 m0, s51, 0x2000
	s_nop 0
	global_load_lds_dwordx4 v[176:177], off
	v_lshl_add_u64 v[176:177], s[30:31], 0, v[160:161]
	s_mov_b32 m0, s29
	s_nop 0
	global_load_lds_dwordx4 v[176:177], off
	s_mov_b32 m0, s35
	s_nop 0
	global_load_lds_dwordx4 v[220:221], off
	s_waitcnt vmcnt(8)
	s_waitcnt lgkmcnt(0)
	s_barrier
; #define PG8_STAGE(bufoff, gbase, voff) do { _Pragma("unroll") for (int _i = 0; _i < 2; ++_i) \
;         __builtin_amdgcn_global_load_lds((const unsigned*)((const char*)(gbase) + (voff)[_i]), (LAS unsigned*)(lds + (bufoff) + ldsw + _i * 8192), 16, 0, 0); } while (0)
; #define PG8_LDA(dst, b, h) do { _Pragma("unroll") for (int m = 0; m < 4; ++m) _Pragma("unroll") for (int k = 0; k < 2; ++k) dst[m][k] = *(const LAS bf16x8*)(lds + PG8_SA(b, h) + aoff + m * 2048 + k * 1024); } while (0)
; #define PG8_LDB(dst, b, h) do { _Pragma("unroll") for (int n = 0; n < 2; ++n) _Pragma("unroll") for (int k = 0; k < 2; ++k) dst[n][k] = *(const LAS bf16x8*)(lds + PG8_SB(b, h) + boff + n * 2048 + k * 1024); } while (0)
; #define PG8_MMA(ai, bj, At, Bt) do { __builtin_amdgcn_s_setprio(1); _Pragma("unroll") for (int m = 0; m < 4; ++m) _Pragma("unroll") for (int n = 0; n < 2; ++n) _Pragma("unroll") for (int k = 0; k < 2; ++k) \
;         acc[ai][bj][m][n] = __builtin_amdgcn_mfma_f32_16x16x32_bf16(Bt[n][k], At[m][k], acc[ai][bj][m][n], 0, 0, 0); __builtin_amdgcn_s_setprio(0); } while (0)
; #define PG8_WAIT_V(n) asm volatile("s_waitcnt vmcnt(" #n ")" ::: "memory")
; #define PG8_WAIT_L(n) asm volatile("s_waitcnt lgkmcnt(" #n ")" ::: "memory")
; #define PG8_BAR __builtin_amdgcn_s_barrier()
; #define PG8_SCHED __builtin_amdgcn_sched_barrier(0)
; template <class Epi>
; __device__ __forceinline__ void gemm_phase(LAS unsigned char* lds, const Gemm g, const StaticOrder& S, const Epi& E, int wave_s) {
;     ...
;             PG8_WAIT_V(8); PG8_WAIT_L(0); PG8_BAR; PG8_MMA(1, 0, At, B0); PG8_MMA(1, 1, At, B1); PG8_BAR; PG8_SCHED;
;             PG8_LDB(B0, 1, 0); PG8_LDB(B1, 1, 1); PG8_SCHED; PG8_LDA(At, 1, 0); PG8_STAGE(PG8_SA(0, 1), a2 + hstepA, voffA);
;             PG8_WAIT_V(8); PG8_WAIT_L(0); PG8_BAR; PG8_MMA(0, 0, At, B0); PG8_MMA(0, 1, At, B1); PG8_BAR; PG8_SCHED;
	s_setprio 1
	s_waitcnt lgkmcnt(0)
	v_mfma_f32_16x16x32_bf16 v[94:97], v[130:133], v[188:191], v[94:97]
	v_mfma_f32_16x16x32_bf16 v[90:93], v[138:141], v[188:191], v[90:93]
	v_mfma_f32_16x16x32_bf16 v[86:89], v[130:133], v[196:199], v[86:89]
	v_mfma_f32_16x16x32_bf16 v[82:85], v[138:141], v[196:199], v[82:85]
	v_mfma_f32_16x16x32_bf16 v[78:81], v[130:133], v[204:207], v[78:81]
	v_mfma_f32_16x16x32_bf16 v[74:77], v[138:141], v[204:207], v[74:77]
	v_mfma_f32_16x16x32_bf16 v[70:73], v[130:133], v[212:215], v[70:73]
	v_mfma_f32_16x16x32_bf16 v[66:69], v[138:141], v[212:215], v[66:69]
	v_mfma_f32_16x16x32_bf16 v[94:97], v[134:137], v[192:195], v[94:97]
	v_mfma_f32_16x16x32_bf16 v[90:93], v[142:145], v[192:195], v[90:93]
	v_mfma_f32_16x16x32_bf16 v[86:89], v[134:137], v[200:203], v[86:89]
	v_mfma_f32_16x16x32_bf16 v[82:85], v[142:145], v[200:203], v[82:85]
	v_mfma_f32_16x16x32_bf16 v[78:81], v[134:137], v[208:211], v[78:81]
	v_mfma_f32_16x16x32_bf16 v[74:77], v[142:145], v[208:211], v[74:77]
	v_mfma_f32_16x16x32_bf16 v[70:73], v[134:137], v[216:219], v[70:73]
	v_mfma_f32_16x16x32_bf16 v[66:69], v[142:145], v[216:219], v[66:69]
	s_setprio 0
	s_setprio 1
	v_mfma_f32_16x16x32_bf16 v[30:33], v[146:149], v[188:191], v[30:33]
	v_mfma_f32_16x16x32_bf16 v[26:29], v[168:171], v[188:191], v[26:29]
	v_mfma_f32_16x16x32_bf16 v[22:25], v[146:149], v[196:199], v[22:25]
	v_mfma_f32_16x16x32_bf16 v[18:21], v[168:171], v[196:199], v[18:21]
	v_mfma_f32_16x16x32_bf16 v[14:17], v[146:149], v[204:207], v[14:17]
	v_mfma_f32_16x16x32_bf16 v[8:11], v[168:171], v[204:207], v[8:11]
	v_mfma_f32_16x16x32_bf16 v[4:7], v[146:149], v[212:215], v[4:7]
	v_mfma_f32_16x16x32_bf16 v[0:3], v[168:171], v[212:215], v[0:3]
	v_mfma_f32_16x16x32_bf16 v[30:33], v[150:153], v[192:195], v[30:33]
	v_mfma_f32_16x16x32_bf16 v[26:29], v[184:187], v[192:195], v[26:29]
	v_mfma_f32_16x16x32_bf16 v[22:25], v[150:153], v[200:203], v[22:25]
	v_mfma_f32_16x16x32_bf16 v[18:21], v[184:187], v[200:203], v[18:21]
	v_mfma_f32_16x16x32_bf16 v[14:17], v[150:153], v[208:211], v[14:17]
	v_mfma_f32_16x16x32_bf16 v[8:11], v[184:187], v[208:211], v[8:11]
	v_mfma_f32_16x16x32_bf16 v[4:7], v[150:153], v[216:219], v[4:7]
	v_mfma_f32_16x16x32_bf16 v[0:3], v[184:187], v[216:219], v[0:3]
	s_setprio 0
	s_barrier
	s_add_i32 s51, 0, 0x18000
	v_add_u32_e32 v12, s51, v166
	s_add_i32 s52, 0, 0x1c000
	ds_read_b128 v[130:133], v12
	ds_read_b128 v[134:137], v12 offset:1024
	ds_read_b128 v[138:141], v12 offset:2048
	ds_read_b128 v[142:145], v12 offset:3072
	v_add_u32_e32 v12, s52, v166
	ds_read_b128 v[188:191], v167 offset:32768
	ds_read_b128 v[192:195], v167 offset:33792
	ds_read_b128 v[196:199], v167 offset:34816
	ds_read_b128 v[200:203], v167 offset:35840
	ds_read_b128 v[204:207], v167 offset:36864
	ds_read_b128 v[208:211], v167 offset:37888
	ds_read_b128 v[212:215], v167 offset:38912
	ds_read_b128 v[216:219], v167 offset:39936
	ds_read_b128 v[146:149], v12
	ds_read_b128 v[150:153], v12 offset:1024
	ds_read_b128 v[168:171], v12 offset:2048
	ds_read_b128 v[184:187], v12 offset:3072
	s_add_u32 s22, s30, 0xc0000
	s_addc_u32 s23, s31, 0
	s_mov_b32 m0, s36
	v_lshl_add_u64 v[222:223], s[22:23], 0, v[160:161]
	global_load_lds_dwordx4 v[222:223], off
	v_lshl_add_u64 v[222:223], s[22:23], 0, v[156:157]
	s_mov_b32 m0, s37
	s_nop 0
	global_load_lds_dwordx4 v[222:223], off
	s_waitcnt vmcnt(8)
	s_cmp_lg_u64 s[10:11], 0
	s_cbranch_scc1 .Lpp_lead_4
	s_waitcnt lgkmcnt(0)
; #define PG8_STAGE(bufoff, gbase, voff) do { _Pragma("unroll") for (int _i = 0; _i < 2; ++_i) \
;         __builtin_amdgcn_global_load_lds((const unsigned*)((const char*)(gbase) + (voff)[_i]), (LAS unsigned*)(lds + (bufoff) + ldsw + _i * 8192), 16, 0, 0); } while (0)
; #define PG8_LDA(dst, b, h) do { _Pragma("unroll") for (int m = 0; m < 4; ++m) _Pragma("unroll") for (int k = 0; k < 2; ++k) dst[m][k] = *(const LAS bf16x8*)(lds + PG8_SA(b, h) + aoff + m * 2048 + k * 1024); } while (0)
; #define PG8_LDB(dst, b, h) do { _Pragma("unroll") for (int n = 0; n < 2; ++n) _Pragma("unroll") for (int k = 0; k < 2; ++k) dst[n][k] = *(const LAS bf16x8*)(lds + PG8_SB(b, h) + boff + n * 2048 + k * 1024); } while (0)
; #define PG8_MMA(ai, bj, At, Bt) do { __builtin_amdgcn_s_setprio(1); _Pragma("unroll") for (int m = 0; m < 4; ++m) _Pragma("unroll") for (int n = 0; n < 2; ++n) _Pragma("unroll") for (int k = 0; k < 2; ++k) \
;         acc[ai][bj][m][n] = __builtin_amdgcn_mfma_f32_16x16x32_bf16(Bt[n][k], At[m][k], acc[ai][bj][m][n], 0, 0, 0); __builtin_amdgcn_s_setprio(0); } while (0)
; #define PG8_WAIT_V(n) asm volatile("s_waitcnt vmcnt(" #n ")" ::: "memory")
; #define PG8_WAIT_L(n) asm volatile("s_waitcnt lgkmcnt(" #n ")" ::: "memory")
; #define PG8_BAR __builtin_amdgcn_s_barrier()
; #define PG8_SCHED __builtin_amdgcn_sched_barrier(0)
; template <class Epi>
; __device__ __forceinline__ void gemm_phase(LAS unsigned char* lds, const Gemm g, const StaticOrder& S, const Epi& E, int wave_s) {
;     ...
;             PG8_LDB(B0, 1, 0); PG8_LDB(B1, 1, 1); PG8_SCHED; PG8_LDA(At, 1, 0); PG8_STAGE(PG8_SA(0, 1), a2 + hstepA, voffA);
;             PG8_WAIT_V(8); PG8_WAIT_L(0); PG8_BAR; PG8_MMA(0, 0, At, B0); PG8_MMA(0, 1, At, B1); PG8_BAR; PG8_SCHED;
;             PG8_LDA(At, 1, 1); PG8_STAGE(PG8_SB(1, 0), b3, voffB); PG8_STAGE(PG8_SB(1, 1), b3 + hstepB, voffB); PG8_STAGE(PG8_SA(1, 0), a3, voffA);
;             PG8_WAIT_V(8); PG8_WAIT_L(0); PG8_BAR; PG8_MMA(1, 0, At, B0); PG8_MMA(1, 1, At, B1); PG8_BAR; PG8_SCHED;
;         }
.Lpp_lead_4:
	s_waitcnt lgkmcnt(4)
	s_barrier
	s_setprio 1
	s_waitcnt lgkmcnt(4)
	v_mfma_f32_16x16x32_bf16 v[126:129], v[130:133], v[188:191], v[126:129]
	v_mfma_f32_16x16x32_bf16 v[122:125], v[138:141], v[188:191], v[122:125]
	v_mfma_f32_16x16x32_bf16 v[118:121], v[130:133], v[196:199], v[118:121]
	v_mfma_f32_16x16x32_bf16 v[114:117], v[138:141], v[196:199], v[114:117]
	v_mfma_f32_16x16x32_bf16 v[110:113], v[130:133], v[204:207], v[110:113]
	v_mfma_f32_16x16x32_bf16 v[106:109], v[138:141], v[204:207], v[106:109]
	v_mfma_f32_16x16x32_bf16 v[102:105], v[130:133], v[212:215], v[102:105]
	v_mfma_f32_16x16x32_bf16 v[98:101], v[138:141], v[212:215], v[98:101]
	v_mfma_f32_16x16x32_bf16 v[126:129], v[134:137], v[192:195], v[126:129]
	v_mfma_f32_16x16x32_bf16 v[122:125], v[142:145], v[192:195], v[122:125]
	v_mfma_f32_16x16x32_bf16 v[118:121], v[134:137], v[200:203], v[118:121]
	v_mfma_f32_16x16x32_bf16 v[114:117], v[142:145], v[200:203], v[114:117]
	v_mfma_f32_16x16x32_bf16 v[110:113], v[134:137], v[208:211], v[110:113]
	v_mfma_f32_16x16x32_bf16 v[106:109], v[142:145], v[208:211], v[106:109]
	v_mfma_f32_16x16x32_bf16 v[102:105], v[134:137], v[216:219], v[102:105]
	v_mfma_f32_16x16x32_bf16 v[98:101], v[142:145], v[216:219], v[98:101]
	s_setprio 0
	s_setprio 1
	s_waitcnt lgkmcnt(0)
	v_mfma_f32_16x16x32_bf16 v[62:65], v[146:149], v[188:191], v[62:65]
	v_mfma_f32_16x16x32_bf16 v[58:61], v[168:171], v[188:191], v[58:61]
	v_mfma_f32_16x16x32_bf16 v[54:57], v[146:149], v[196:199], v[54:57]
	v_mfma_f32_16x16x32_bf16 v[50:53], v[168:171], v[196:199], v[50:53]
	v_mfma_f32_16x16x32_bf16 v[46:49], v[146:149], v[204:207], v[46:49]
	v_mfma_f32_16x16x32_bf16 v[42:45], v[168:171], v[204:207], v[42:45]
	v_mfma_f32_16x16x32_bf16 v[38:41], v[146:149], v[212:215], v[38:41]
	v_mfma_f32_16x16x32_bf16 v[34:37], v[168:171], v[212:215], v[34:37]
	v_mfma_f32_16x16x32_bf16 v[62:65], v[150:153], v[192:195], v[62:65]
	v_mfma_f32_16x16x32_bf16 v[58:61], v[184:187], v[192:195], v[58:61]
	v_mfma_f32_16x16x32_bf16 v[54:57], v[150:153], v[200:203], v[54:57]
	v_mfma_f32_16x16x32_bf16 v[50:53], v[184:187], v[200:203], v[50:53]
	v_mfma_f32_16x16x32_bf16 v[46:49], v[150:153], v[208:211], v[46:49]
	v_mfma_f32_16x16x32_bf16 v[42:45], v[184:187], v[208:211], v[42:45]
	v_mfma_f32_16x16x32_bf16 v[38:41], v[150:153], v[216:219], v[38:41]
	v_mfma_f32_16x16x32_bf16 v[34:37], v[184:187], v[216:219], v[34:37]
	s_setprio 0
	s_barrier
	s_add_i32 s22, s51, s25
	v_lshl_add_u64 v[172:173], v[172:173], 0, s[84:85]
	s_mov_b32 m0, s22
	ds_read_b128 v[188:191], v167 offset:49152
	ds_read_b128 v[192:195], v167 offset:50176
	ds_read_b128 v[196:199], v167 offset:51200
	ds_read_b128 v[200:203], v167 offset:52224
	ds_read_b128 v[204:207], v167 offset:53248
	ds_read_b128 v[208:211], v167 offset:54272
	ds_read_b128 v[212:215], v167 offset:55296
	ds_read_b128 v[216:219], v167 offset:56320
	global_load_lds_dwordx4 v[172:173], off
	s_add_i32 m0, s22, 0x2000
	s_add_u32 s22, s26, 0x18080
	v_lshl_add_u64 v[172:173], v[174:175], 0, s[84:85]
	s_addc_u32 s23, s27, 0
	s_add_i32 s26, s52, s25
	global_load_lds_dwordx4 v[172:173], off
	v_lshl_add_u64 v[172:173], s[22:23], 0, v[158:159]
	s_mov_b32 m0, s26
	s_nop 0
	global_load_lds_dwordx4 v[172:173], off
	v_lshl_add_u64 v[172:173], s[22:23], 0, v[154:155]
	s_add_i32 m0, s26, 0x2000
	s_nop 0
	global_load_lds_dwordx4 v[172:173], off
	v_lshl_add_u64 v[172:173], v[176:177], 0, s[84:85]
	s_mov_b32 m0, s41
	s_nop 0
	global_load_lds_dwordx4 v[172:173], off
	v_lshl_add_u64 v[172:173], v[220:221], 0, s[84:85]
	s_mov_b32 m0, s42
	s_nop 0
	global_load_lds_dwordx4 v[172:173], off
	s_waitcnt vmcnt(8)
	s_waitcnt lgkmcnt(0)
	s_barrier
	s_setprio 1
	s_waitcnt lgkmcnt(0)
	v_mfma_f32_16x16x32_bf16 v[94:97], v[130:133], v[188:191], v[94:97]
	v_mfma_f32_16x16x32_bf16 v[90:93], v[138:141], v[188:191], v[90:93]
	v_mfma_f32_16x16x32_bf16 v[86:89], v[130:133], v[196:199], v[86:89]
	v_mfma_f32_16x16x32_bf16 v[82:85], v[138:141], v[196:199], v[82:85]
	v_mfma_f32_16x16x32_bf16 v[78:81], v[130:133], v[204:207], v[78:81]
	v_mfma_f32_16x16x32_bf16 v[74:77], v[138:141], v[204:207], v[74:77]
	v_mfma_f32_16x16x32_bf16 v[70:73], v[130:133], v[212:215], v[70:73]
	v_mfma_f32_16x16x32_bf16 v[66:69], v[138:141], v[212:215], v[66:69]
	v_mfma_f32_16x16x32_bf16 v[94:97], v[134:137], v[192:195], v[94:97]
	v_mfma_f32_16x16x32_bf16 v[90:93], v[142:145], v[192:195], v[90:93]
	v_mfma_f32_16x16x32_bf16 v[86:89], v[134:137], v[200:203], v[86:89]
	v_mfma_f32_16x16x32_bf16 v[82:85], v[142:145], v[200:203], v[82:85]
	v_mfma_f32_16x16x32_bf16 v[78:81], v[134:137], v[208:211], v[78:81]
	v_mfma_f32_16x16x32_bf16 v[74:77], v[142:145], v[208:211], v[74:77]
	v_mfma_f32_16x16x32_bf16 v[70:73], v[134:137], v[216:219], v[70:73]
	v_mfma_f32_16x16x32_bf16 v[66:69], v[142:145], v[216:219], v[66:69]
	s_setprio 0
	s_setprio 1
	v_mfma_f32_16x16x32_bf16 v[30:33], v[146:149], v[188:191], v[30:33]
	v_mfma_f32_16x16x32_bf16 v[26:29], v[168:171], v[188:191], v[26:29]
	v_mfma_f32_16x16x32_bf16 v[22:25], v[146:149], v[196:199], v[22:25]
	v_mfma_f32_16x16x32_bf16 v[18:21], v[168:171], v[196:199], v[18:21]
	v_mfma_f32_16x16x32_bf16 v[14:17], v[146:149], v[204:207], v[14:17]
	v_mfma_f32_16x16x32_bf16 v[8:11], v[168:171], v[204:207], v[8:11]
	v_mfma_f32_16x16x32_bf16 v[4:7], v[146:149], v[212:215], v[4:7]
	v_mfma_f32_16x16x32_bf16 v[0:3], v[168:171], v[212:215], v[0:3]
	v_mfma_f32_16x16x32_bf16 v[30:33], v[150:153], v[192:195], v[30:33]
	v_mfma_f32_16x16x32_bf16 v[26:29], v[184:187], v[192:195], v[26:29]
	v_mfma_f32_16x16x32_bf16 v[22:25], v[150:153], v[200:203], v[22:25]
	v_mfma_f32_16x16x32_bf16 v[18:21], v[184:187], v[200:203], v[18:21]
	v_mfma_f32_16x16x32_bf16 v[14:17], v[150:153], v[208:211], v[14:17]
	v_mfma_f32_16x16x32_bf16 v[8:11], v[184:187], v[208:211], v[8:11]
	v_mfma_f32_16x16x32_bf16 v[4:7], v[150:153], v[216:219], v[4:7]
	v_mfma_f32_16x16x32_bf16 v[0:3], v[184:187], v[216:219], v[0:3]
	s_setprio 0
	s_barrier
	s_add_i32 s50, s50, 2
	s_add_u32 s48, s48, 0x100
	s_addc_u32 s49, s49, 0
	s_cmp_gt_u32 s50, 3
	s_mov_b64 s[22:23], s[6:7]
	s_cbranch_scc0 .LBB0_343
	s_and_b64 vcc, exec, s[10:11]
	s_cbranch_vccz .LBB0_346
	s_barrier

; #define PG8_STAGE(bufoff, gbase, voff) do { _Pragma("unroll") for (int _i = 0; _i < 2; ++_i) \
;         __builtin_amdgcn_global_load_lds((const unsigned*)((const char*)(gbase) + (voff)[_i]), (LAS unsigned*)(lds + (bufoff) + ldsw + _i * 8192), 16, 0, 0); } while (0)
; #define PG8_LDA(dst, b, h) do { _Pragma("unroll") for (int m = 0; m < 4; ++m) _Pragma("unroll") for (int k = 0; k < 2; ++k) dst[m][k] = *(const LAS bf16x8*)(lds + PG8_SA(b, h) + aoff + m * 2048 + k * 1024); } while (0)
; #define PG8_LDB(dst, b, h) do { _Pragma("unroll") for (int n = 0; n < 2; ++n) _Pragma("unroll") for (int k = 0; k < 2; ++k) dst[n][k] = *(const LAS bf16x8*)(lds + PG8_SB(b, h) + boff + n * 2048 + k * 1024); } while (0)
; #define PG8_MMA(ai, bj, At, Bt) do { __builtin_amdgcn_s_setprio(1); _Pragma("unroll") for (int m = 0; m < 4; ++m) _Pragma("unroll") for (int n = 0; n < 2; ++n) _Pragma("unroll") for (int k = 0; k < 2; ++k) \
;         acc[ai][bj][m][n] = __builtin_amdgcn_mfma_f32_16x16x32_bf16(Bt[n][k], At[m][k], acc[ai][bj][m][n], 0, 0, 0); __builtin_amdgcn_s_setprio(0); } while (0)
; #define PG8_WAIT_V(n) asm volatile("s_waitcnt vmcnt(" #n ")" ::: "memory")
; #define PG8_WAIT_L(n) asm volatile("s_waitcnt lgkmcnt(" #n ")" ::: "memory")
; #define PG8_BAR __builtin_amdgcn_s_barrier()
; #define PG8_SCHED __builtin_amdgcn_sched_barrier(0)
; template <class Epi>
; __device__ __forceinline__ void gemm_phase(LAS unsigned char* lds, const Gemm g, const StaticOrder& S, const Epi& E, int wave_s) {
;     ...
;             PG8_LDB(B0, 0, 0); PG8_LDB(B1, 0, 1); PG8_SCHED; PG8_LDA(At, 0, 0); PG8_STAGE(PG8_SA(1, 1), a1 + hstepA, voffA);
;             PG8_WAIT_V(8); PG8_WAIT_L(0); PG8_BAR; PG8_MMA(0, 0, At, B0); PG8_MMA(0, 1, At, B1); PG8_BAR; PG8_SCHED;
;             PG8_LDA(At, 0, 1); PG8_STAGE(PG8_SB(0, 0), b2, voffB); PG8_STAGE(PG8_SB(0, 1), b2 + hstepB, voffB); PG8_STAGE(PG8_SA(0, 0), a2, voffA);
;             PG8_WAIT_V(8); PG8_WAIT_L(0); PG8_BAR; PG8_MMA(1, 0, At, B0); PG8_MMA(1, 1, At, B1); PG8_BAR; PG8_SCHED;
.LBB0_916:
	s_add_u32 s40, s8, 0xfffc0080
	s_addc_u32 s41, s9, -1
	s_add_i32 s58, 0, 0x10000
	s_cmp_eq_u32 s83, 12
	s_cselect_b32 s43, s53, s41
	s_cselect_b32 s42, s54, s40
	s_cselect_b32 s41, s64, s69
	s_cselect_b32 s40, s65, s68
	s_add_i32 s70, 0, 0x14000
	v_add_u32_e32 v156, s58, v167
	v_add_u32_e32 v164, s70, v167
	ds_read_b128 v[130:133], v156
	ds_read_b128 v[134:137], v156 offset:1024
	ds_read_b128 v[152:155], v156 offset:2048
	ds_read_b128 v[156:159], v156 offset:3072
	ds_read_b128 v[186:189], v247
	ds_read_b128 v[190:193], v247 offset:1024
	ds_read_b128 v[194:197], v247 offset:2048
	ds_read_b128 v[198:201], v247 offset:3072
	ds_read_b128 v[202:205], v247 offset:4096
	ds_read_b128 v[208:211], v247 offset:5120
	ds_read_b128 v[212:215], v247 offset:6144
	ds_read_b128 v[222:225], v247 offset:7168
	ds_read_b128 v[160:163], v164
	ds_read_b128 v[170:173], v164 offset:1024
	ds_read_b128 v[178:181], v164 offset:2048
	ds_read_b128 v[182:185], v164 offset:3072
	v_lshl_add_u64 v[164:165], s[8:9], 0, v[148:149]
	s_add_i32 m0, s37, 0xc000
	global_load_lds_dwordx4 v[164:165], off
	v_lshl_add_u64 v[164:165], s[8:9], 0, v[150:151]
	s_add_i32 m0, s37, 0xe000
	s_nop 0
	global_load_lds_dwordx4 v[164:165], off
	s_waitcnt vmcnt(8)
	s_cmp_lg_u64 s[22:23], 0
	s_cbranch_scc1 .Lpp_lead_5
	s_waitcnt lgkmcnt(0)
.Lpp_lead_5:
	s_waitcnt lgkmcnt(4)
	s_barrier
	s_setprio 1
	s_waitcnt lgkmcnt(4)
	v_mfma_f32_16x16x32_bf16 v[106:109], v[130:133], v[186:189], v[106:109]
	v_mfma_f32_16x16x32_bf16 v[114:117], v[152:155], v[186:189], v[114:117]
	v_mfma_f32_16x16x32_bf16 v[98:101], v[130:133], v[194:197], v[98:101]
	v_mfma_f32_16x16x32_bf16 v[110:113], v[152:155], v[194:197], v[110:113]
	v_mfma_f32_16x16x32_bf16 v[94:97], v[130:133], v[202:205], v[94:97]
	v_mfma_f32_16x16x32_bf16 v[102:105], v[152:155], v[202:205], v[102:105]
	v_mfma_f32_16x16x32_bf16 v[90:93], v[130:133], v[212:215], v[90:93]
	v_mfma_f32_16x16x32_bf16 v[126:129], v[152:155], v[212:215], v[126:129]
	v_mfma_f32_16x16x32_bf16 v[106:109], v[134:137], v[190:193], v[106:109]
	v_mfma_f32_16x16x32_bf16 v[114:117], v[156:159], v[190:193], v[114:117]
	v_mfma_f32_16x16x32_bf16 v[98:101], v[134:137], v[198:201], v[98:101]
	v_mfma_f32_16x16x32_bf16 v[110:113], v[156:159], v[198:201], v[110:113]
	v_mfma_f32_16x16x32_bf16 v[94:97], v[134:137], v[208:211], v[94:97]
	v_mfma_f32_16x16x32_bf16 v[102:105], v[156:159], v[208:211], v[102:105]
	v_mfma_f32_16x16x32_bf16 v[90:93], v[134:137], v[222:225], v[90:93]
	v_mfma_f32_16x16x32_bf16 v[126:129], v[156:159], v[222:225], v[126:129]
	s_setprio 0
	s_setprio 1
	s_waitcnt lgkmcnt(0)
	v_mfma_f32_16x16x32_bf16 v[62:65], v[160:163], v[186:189], v[62:65]
	v_mfma_f32_16x16x32_bf16 v[34:37], v[178:181], v[186:189], v[34:37]
	v_mfma_f32_16x16x32_bf16 v[58:61], v[160:163], v[194:197], v[58:61]
	v_mfma_f32_16x16x32_bf16 v[30:33], v[178:181], v[194:197], v[30:33]
	v_mfma_f32_16x16x32_bf16 v[54:57], v[160:163], v[202:205], v[54:57]
	v_mfma_f32_16x16x32_bf16 v[26:29], v[178:181], v[202:205], v[26:29]
	v_mfma_f32_16x16x32_bf16 v[50:53], v[160:163], v[212:215], v[50:53]
	v_mfma_f32_16x16x32_bf16 v[22:25], v[178:181], v[212:215], v[22:25]
	v_mfma_f32_16x16x32_bf16 v[62:65], v[170:173], v[190:193], v[62:65]
	v_mfma_f32_16x16x32_bf16 v[34:37], v[182:185], v[190:193], v[34:37]
	v_mfma_f32_16x16x32_bf16 v[58:61], v[170:173], v[198:201], v[58:61]
	v_mfma_f32_16x16x32_bf16 v[30:33], v[182:185], v[198:201], v[30:33]
	v_mfma_f32_16x16x32_bf16 v[54:57], v[170:173], v[208:211], v[54:57]
	v_mfma_f32_16x16x32_bf16 v[26:29], v[182:185], v[208:211], v[26:29]
	v_mfma_f32_16x16x32_bf16 v[50:53], v[170:173], v[222:225], v[50:53]
	v_mfma_f32_16x16x32_bf16 v[22:25], v[182:185], v[222:225], v[22:25]
	s_setprio 0
	s_barrier
	s_add_i32 s58, s58, s36
	v_lshl_add_u64 v[164:165], s[40:41], 0, v[12:13]
	s_mov_b32 m0, s58
	ds_read_b128 v[186:189], v247 offset:16384
	ds_read_b128 v[190:193], v247 offset:17408
	ds_read_b128 v[194:197], v247 offset:18432
	ds_read_b128 v[198:201], v247 offset:19456
	ds_read_b128 v[202:205], v247 offset:20480
	ds_read_b128 v[208:211], v247 offset:21504
	ds_read_b128 v[212:215], v247 offset:22528
	ds_read_b128 v[222:225], v247 offset:23552
	global_load_lds_dwordx4 v[164:165], off
	s_add_i32 m0, s58, 0x2000
	s_add_u32 s58, s40, 0x40000
	v_lshl_add_u64 v[174:175], s[40:41], 0, v[138:139]
	s_addc_u32 s59, s41, 0
	s_add_i32 s70, s70, s36
	global_load_lds_dwordx4 v[174:175], off
	v_lshl_add_u64 v[176:177], s[58:59], 0, v[12:13]
	s_mov_b32 m0, s70
	v_lshl_add_u64 v[240:241], s[42:43], 0, v[140:141]
	global_load_lds_dwordx4 v[176:177], off
	v_lshl_add_u64 v[176:177], s[58:59], 0, v[138:139]
	s_add_i32 m0, s70, 0x2000
	s_nop 0
	global_load_lds_dwordx4 v[176:177], off
	v_lshl_add_u64 v[176:177], s[42:43], 0, v[142:143]
	s_mov_b32 m0, s37
	s_nop 0
	global_load_lds_dwordx4 v[176:177], off
	s_mov_b32 m0, s44
	s_nop 0
	global_load_lds_dwordx4 v[240:241], off
	s_waitcnt vmcnt(8)
	s_waitcnt lgkmcnt(0)
	s_barrier
; #define PG8_STAGE(bufoff, gbase, voff) do { _Pragma("unroll") for (int _i = 0; _i < 2; ++_i) \
;         __builtin_amdgcn_global_load_lds((const unsigned*)((const char*)(gbase) + (voff)[_i]), (LAS unsigned*)(lds + (bufoff) + ldsw + _i * 8192), 16, 0, 0); } while (0)
; #define PG8_LDA(dst, b, h) do { _Pragma("unroll") for (int m = 0; m < 4; ++m) _Pragma("unroll") for (int k = 0; k < 2; ++k) dst[m][k] = *(const LAS bf16x8*)(lds + PG8_SA(b, h) + aoff + m * 2048 + k * 1024); } while (0)
; #define PG8_LDB(dst, b, h) do { _Pragma("unroll") for (int n = 0; n < 2; ++n) _Pragma("unroll") for (int k = 0; k < 2; ++k) dst[n][k] = *(const LAS bf16x8*)(lds + PG8_SB(b, h) + boff + n * 2048 + k * 1024); } while (0)
; #define PG8_MMA(ai, bj, At, Bt) do { __builtin_amdgcn_s_setprio(1); _Pragma("unroll") for (int m = 0; m < 4; ++m) _Pragma("unroll") for (int n = 0; n < 2; ++n) _Pragma("unroll") for (int k = 0; k < 2; ++k) \
;         acc[ai][bj][m][n] = __builtin_amdgcn_mfma_f32_16x16x32_bf16(Bt[n][k], At[m][k], acc[ai][bj][m][n], 0, 0, 0); __builtin_amdgcn_s_setprio(0); } while (0)
; #define PG8_WAIT_V(n) asm volatile("s_waitcnt vmcnt(" #n ")" ::: "memory")
; #define PG8_WAIT_L(n) asm volatile("s_waitcnt lgkmcnt(" #n ")" ::: "memory")
; #define PG8_BAR __builtin_amdgcn_s_barrier()
; #define PG8_SCHED __builtin_amdgcn_sched_barrier(0)
; template <class Epi>
; __device__ __forceinline__ void gemm_phase(LAS unsigned char* lds, const Gemm g, const StaticOrder& S, const Epi& E, int wave_s) {
;     ...
;             PG8_WAIT_V(8); PG8_WAIT_L(0); PG8_BAR; PG8_MMA(1, 0, At, B0); PG8_MMA(1, 1, At, B1); PG8_BAR; PG8_SCHED;
;             PG8_LDB(B0, 1, 0); PG8_LDB(B1, 1, 1); PG8_SCHED; PG8_LDA(At, 1, 0); PG8_STAGE(PG8_SA(0, 1), a2 + hstepA, voffA);
;             PG8_WAIT_V(8); PG8_WAIT_L(0); PG8_BAR; PG8_MMA(0, 0, At, B0); PG8_MMA(0, 1, At, B1); PG8_BAR; PG8_SCHED;
	s_setprio 1
	s_waitcnt lgkmcnt(0)
	v_mfma_f32_16x16x32_bf16 v[86:89], v[130:133], v[186:189], v[86:89]
	v_mfma_f32_16x16x32_bf16 v[122:125], v[152:155], v[186:189], v[122:125]
	v_mfma_f32_16x16x32_bf16 v[82:85], v[130:133], v[194:197], v[82:85]
	v_mfma_f32_16x16x32_bf16 v[118:121], v[152:155], v[194:197], v[118:121]
	v_mfma_f32_16x16x32_bf16 v[78:81], v[130:133], v[202:205], v[78:81]
	v_mfma_f32_16x16x32_bf16 v[70:73], v[152:155], v[202:205], v[70:73]
	v_mfma_f32_16x16x32_bf16 v[74:77], v[130:133], v[212:215], v[74:77]
	v_mfma_f32_16x16x32_bf16 v[66:69], v[152:155], v[212:215], v[66:69]
	v_mfma_f32_16x16x32_bf16 v[86:89], v[134:137], v[190:193], v[86:89]
	v_mfma_f32_16x16x32_bf16 v[122:125], v[156:159], v[190:193], v[122:125]
	v_mfma_f32_16x16x32_bf16 v[82:85], v[134:137], v[198:201], v[82:85]
	v_mfma_f32_16x16x32_bf16 v[118:121], v[156:159], v[198:201], v[118:121]
	v_mfma_f32_16x16x32_bf16 v[78:81], v[134:137], v[208:211], v[78:81]
	v_mfma_f32_16x16x32_bf16 v[70:73], v[156:159], v[208:211], v[70:73]
	v_mfma_f32_16x16x32_bf16 v[74:77], v[134:137], v[222:225], v[74:77]
	v_mfma_f32_16x16x32_bf16 v[66:69], v[156:159], v[222:225], v[66:69]
	s_setprio 0
	s_setprio 1
	v_mfma_f32_16x16x32_bf16 v[46:49], v[160:163], v[186:189], v[46:49]
	v_mfma_f32_16x16x32_bf16 v[14:17], v[178:181], v[186:189], v[14:17]
	v_mfma_f32_16x16x32_bf16 v[42:45], v[160:163], v[194:197], v[42:45]
	v_mfma_f32_16x16x32_bf16 v[8:11], v[178:181], v[194:197], v[8:11]
	v_mfma_f32_16x16x32_bf16 v[38:41], v[160:163], v[202:205], v[38:41]
	v_mfma_f32_16x16x32_bf16 v[4:7], v[178:181], v[202:205], v[4:7]
	v_mfma_f32_16x16x32_bf16 v[18:21], v[160:163], v[212:215], v[18:21]
	v_mfma_f32_16x16x32_bf16 v[0:3], v[178:181], v[212:215], v[0:3]
	v_mfma_f32_16x16x32_bf16 v[46:49], v[170:173], v[190:193], v[46:49]
	v_mfma_f32_16x16x32_bf16 v[14:17], v[182:185], v[190:193], v[14:17]
	v_mfma_f32_16x16x32_bf16 v[42:45], v[170:173], v[198:201], v[42:45]
	v_mfma_f32_16x16x32_bf16 v[8:11], v[182:185], v[198:201], v[8:11]
	v_mfma_f32_16x16x32_bf16 v[38:41], v[170:173], v[208:211], v[38:41]
	v_mfma_f32_16x16x32_bf16 v[4:7], v[182:185], v[208:211], v[4:7]
	v_mfma_f32_16x16x32_bf16 v[18:21], v[170:173], v[222:225], v[18:21]
	v_mfma_f32_16x16x32_bf16 v[0:3], v[182:185], v[222:225], v[0:3]
	s_setprio 0
	s_barrier
	s_add_i32 s58, 0, 0x18000
	s_add_i32 s59, 0, 0x1c000
	v_add_u32_e32 v156, s58, v167
	v_add_u32_e32 v182, s59, v167
	ds_read_b128 v[130:133], v156
	ds_read_b128 v[134:137], v156 offset:1024
	ds_read_b128 v[152:155], v156 offset:2048
	ds_read_b128 v[156:159], v156 offset:3072
	ds_read_b128 v[186:189], v247 offset:32768
	ds_read_b128 v[190:193], v247 offset:33792
	ds_read_b128 v[194:197], v247 offset:34816
	ds_read_b128 v[198:201], v247 offset:35840
	ds_read_b128 v[202:205], v247 offset:36864
	ds_read_b128 v[208:211], v247 offset:37888
	ds_read_b128 v[212:215], v247 offset:38912
	ds_read_b128 v[222:225], v247 offset:39936
	ds_read_b128 v[160:163], v182
	ds_read_b128 v[170:173], v182 offset:1024
	ds_read_b128 v[178:181], v182 offset:2048
	ds_read_b128 v[182:185], v182 offset:3072
	s_add_u32 s42, s42, 0x40000
	s_addc_u32 s43, s43, 0
	s_mov_b32 m0, s45
	v_lshl_add_u64 v[250:251], s[42:43], 0, v[142:143]
	global_load_lds_dwordx4 v[250:251], off
	v_lshl_add_u64 v[250:251], s[42:43], 0, v[140:141]
	s_mov_b32 m0, s46
	s_nop 0
	global_load_lds_dwordx4 v[250:251], off
	s_waitcnt vmcnt(8)
	s_cmp_lg_u64 s[22:23], 0
	s_cbranch_scc1 .Lpp_lead_6
	s_waitcnt lgkmcnt(0)
; #define PG8_STAGE(bufoff, gbase, voff) do { _Pragma("unroll") for (int _i = 0; _i < 2; ++_i) \
;         __builtin_amdgcn_global_load_lds((const unsigned*)((const char*)(gbase) + (voff)[_i]), (LAS unsigned*)(lds + (bufoff) + ldsw + _i * 8192), 16, 0, 0); } while (0)
; #define PG8_LDA(dst, b, h) do { _Pragma("unroll") for (int m = 0; m < 4; ++m) _Pragma("unroll") for (int k = 0; k < 2; ++k) dst[m][k] = *(const LAS bf16x8*)(lds + PG8_SA(b, h) + aoff + m * 2048 + k * 1024); } while (0)
; #define PG8_MMA(ai, bj, At, Bt) do { __builtin_amdgcn_s_setprio(1); _Pragma("unroll") for (int m = 0; m < 4; ++m) _Pragma("unroll") for (int n = 0; n < 2; ++n) _Pragma("unroll") for (int k = 0; k < 2; ++k) \
;         acc[ai][bj][m][n] = __builtin_amdgcn_mfma_f32_16x16x32_bf16(Bt[n][k], At[m][k], acc[ai][bj][m][n], 0, 0, 0); __builtin_amdgcn_s_setprio(0); } while (0)
; #define PG8_WAIT_V(n) asm volatile("s_waitcnt vmcnt(" #n ")" ::: "memory")
; #define PG8_WAIT_L(n) asm volatile("s_waitcnt lgkmcnt(" #n ")" ::: "memory")
; #define PG8_BAR __builtin_amdgcn_s_barrier()
; #define PG8_SCHED __builtin_amdgcn_sched_barrier(0)
; template <class Epi>
; __device__ __forceinline__ void gemm_phase(LAS unsigned char* lds, const Gemm g, const StaticOrder& S, const Epi& E, int wave_s) {
;     ...
;             PG8_WAIT_V(8); PG8_WAIT_L(0); PG8_BAR; PG8_MMA(0, 0, At, B0); PG8_MMA(0, 1, At, B1); PG8_BAR; PG8_SCHED;
;             PG8_LDA(At, 1, 1); PG8_STAGE(PG8_SB(1, 0), b3, voffB); PG8_STAGE(PG8_SB(1, 1), b3 + hstepB, voffB); PG8_STAGE(PG8_SA(1, 0), a3, voffA);
;             PG8_WAIT_V(8); PG8_WAIT_L(0); PG8_BAR; PG8_MMA(1, 0, At, B0); PG8_MMA(1, 1, At, B1); PG8_BAR; PG8_SCHED;
;         }
;         if (wr == 0) PG8_BAR;
.Lpp_lead_6:
	s_waitcnt lgkmcnt(4)
	s_barrier
	s_setprio 1
	s_waitcnt lgkmcnt(4)
	v_mfma_f32_16x16x32_bf16 v[106:109], v[130:133], v[186:189], v[106:109]
	v_mfma_f32_16x16x32_bf16 v[114:117], v[152:155], v[186:189], v[114:117]
	v_mfma_f32_16x16x32_bf16 v[98:101], v[130:133], v[194:197], v[98:101]
	v_mfma_f32_16x16x32_bf16 v[110:113], v[152:155], v[194:197], v[110:113]
	v_mfma_f32_16x16x32_bf16 v[94:97], v[130:133], v[202:205], v[94:97]
	v_mfma_f32_16x16x32_bf16 v[102:105], v[152:155], v[202:205], v[102:105]
	v_mfma_f32_16x16x32_bf16 v[90:93], v[130:133], v[212:215], v[90:93]
	v_mfma_f32_16x16x32_bf16 v[126:129], v[152:155], v[212:215], v[126:129]
	v_mfma_f32_16x16x32_bf16 v[106:109], v[134:137], v[190:193], v[106:109]
	v_mfma_f32_16x16x32_bf16 v[114:117], v[156:159], v[190:193], v[114:117]
	v_mfma_f32_16x16x32_bf16 v[98:101], v[134:137], v[198:201], v[98:101]
	v_mfma_f32_16x16x32_bf16 v[110:113], v[156:159], v[198:201], v[110:113]
	v_mfma_f32_16x16x32_bf16 v[94:97], v[134:137], v[208:211], v[94:97]
	v_mfma_f32_16x16x32_bf16 v[102:105], v[156:159], v[208:211], v[102:105]
	v_mfma_f32_16x16x32_bf16 v[90:93], v[134:137], v[222:225], v[90:93]
	v_mfma_f32_16x16x32_bf16 v[126:129], v[156:159], v[222:225], v[126:129]
	s_setprio 0
	s_setprio 1
	s_waitcnt lgkmcnt(0)
	v_mfma_f32_16x16x32_bf16 v[62:65], v[160:163], v[186:189], v[62:65]
	v_mfma_f32_16x16x32_bf16 v[34:37], v[178:181], v[186:189], v[34:37]
	v_mfma_f32_16x16x32_bf16 v[58:61], v[160:163], v[194:197], v[58:61]
	v_mfma_f32_16x16x32_bf16 v[30:33], v[178:181], v[194:197], v[30:33]
	v_mfma_f32_16x16x32_bf16 v[54:57], v[160:163], v[202:205], v[54:57]
	v_mfma_f32_16x16x32_bf16 v[26:29], v[178:181], v[202:205], v[26:29]
	v_mfma_f32_16x16x32_bf16 v[50:53], v[160:163], v[212:215], v[50:53]
	v_mfma_f32_16x16x32_bf16 v[22:25], v[178:181], v[212:215], v[22:25]
	v_mfma_f32_16x16x32_bf16 v[62:65], v[170:173], v[190:193], v[62:65]
	v_mfma_f32_16x16x32_bf16 v[34:37], v[182:185], v[190:193], v[34:37]
	v_mfma_f32_16x16x32_bf16 v[58:61], v[170:173], v[198:201], v[58:61]
	v_mfma_f32_16x16x32_bf16 v[30:33], v[182:185], v[198:201], v[30:33]
	v_mfma_f32_16x16x32_bf16 v[54:57], v[170:173], v[208:211], v[54:57]
	v_mfma_f32_16x16x32_bf16 v[26:29], v[182:185], v[208:211], v[26:29]
	v_mfma_f32_16x16x32_bf16 v[50:53], v[170:173], v[222:225], v[50:53]
	v_mfma_f32_16x16x32_bf16 v[22:25], v[182:185], v[222:225], v[22:25]
	s_setprio 0
	s_barrier
	s_add_i32 s42, s58, s36
	v_lshl_add_u64 v[164:165], v[164:165], 0, s[84:85]
	s_mov_b32 m0, s42
	ds_read_b128 v[186:189], v247 offset:49152
	ds_read_b128 v[190:193], v247 offset:50176
	ds_read_b128 v[194:197], v247 offset:51200
	ds_read_b128 v[198:201], v247 offset:52224
	ds_read_b128 v[202:205], v247 offset:53248
	ds_read_b128 v[208:211], v247 offset:54272
	ds_read_b128 v[212:215], v247 offset:55296
	ds_read_b128 v[222:225], v247 offset:56320
	global_load_lds_dwordx4 v[164:165], off
	s_add_i32 m0, s42, 0x2000
	s_add_u32 s40, s40, 0x40080
	v_lshl_add_u64 v[164:165], v[174:175], 0, s[84:85]
	s_addc_u32 s41, s41, 0
	s_add_i32 s42, s59, s36
	global_load_lds_dwordx4 v[164:165], off
	v_lshl_add_u64 v[164:165], s[40:41], 0, v[12:13]
	s_mov_b32 m0, s42
	s_nop 0
	global_load_lds_dwordx4 v[164:165], off
	v_lshl_add_u64 v[164:165], s[40:41], 0, v[138:139]
	s_add_i32 m0, s42, 0x2000
	s_nop 0
	global_load_lds_dwordx4 v[164:165], off
	v_lshl_add_u64 v[164:165], v[176:177], 0, s[84:85]
	s_mov_b32 m0, s50
	s_nop 0
	global_load_lds_dwordx4 v[164:165], off
	v_lshl_add_u64 v[164:165], v[240:241], 0, s[84:85]
	s_mov_b32 m0, s51
	s_nop 0
	global_load_lds_dwordx4 v[164:165], off
	s_waitcnt vmcnt(8)
	s_waitcnt lgkmcnt(0)
	s_barrier
	s_setprio 1
	s_waitcnt lgkmcnt(0)
	v_mfma_f32_16x16x32_bf16 v[86:89], v[130:133], v[186:189], v[86:89]
	v_mfma_f32_16x16x32_bf16 v[122:125], v[152:155], v[186:189], v[122:125]
	v_mfma_f32_16x16x32_bf16 v[82:85], v[130:133], v[194:197], v[82:85]
	v_mfma_f32_16x16x32_bf16 v[118:121], v[152:155], v[194:197], v[118:121]
	v_mfma_f32_16x16x32_bf16 v[78:81], v[130:133], v[202:205], v[78:81]
	v_mfma_f32_16x16x32_bf16 v[70:73], v[152:155], v[202:205], v[70:73]
	v_mfma_f32_16x16x32_bf16 v[74:77], v[130:133], v[212:215], v[74:77]
	v_mfma_f32_16x16x32_bf16 v[66:69], v[152:155], v[212:215], v[66:69]
	v_mfma_f32_16x16x32_bf16 v[86:89], v[134:137], v[190:193], v[86:89]
	v_mfma_f32_16x16x32_bf16 v[122:125], v[156:159], v[190:193], v[122:125]
	v_mfma_f32_16x16x32_bf16 v[82:85], v[134:137], v[198:201], v[82:85]
	v_mfma_f32_16x16x32_bf16 v[118:121], v[156:159], v[198:201], v[118:121]
	v_mfma_f32_16x16x32_bf16 v[78:81], v[134:137], v[208:211], v[78:81]
	v_mfma_f32_16x16x32_bf16 v[70:73], v[156:159], v[208:211], v[70:73]
	v_mfma_f32_16x16x32_bf16 v[74:77], v[134:137], v[222:225], v[74:77]
	v_mfma_f32_16x16x32_bf16 v[66:69], v[156:159], v[222:225], v[66:69]
	s_setprio 0
	s_setprio 1
	v_mfma_f32_16x16x32_bf16 v[46:49], v[160:163], v[186:189], v[46:49]
	v_mfma_f32_16x16x32_bf16 v[14:17], v[178:181], v[186:189], v[14:17]
	v_mfma_f32_16x16x32_bf16 v[42:45], v[160:163], v[194:197], v[42:45]
	v_mfma_f32_16x16x32_bf16 v[8:11], v[178:181], v[194:197], v[8:11]
	v_mfma_f32_16x16x32_bf16 v[38:41], v[160:163], v[202:205], v[38:41]
	v_mfma_f32_16x16x32_bf16 v[4:7], v[178:181], v[202:205], v[4:7]
	v_mfma_f32_16x16x32_bf16 v[18:21], v[160:163], v[212:215], v[18:21]
	v_mfma_f32_16x16x32_bf16 v[0:3], v[178:181], v[212:215], v[0:3]
	v_mfma_f32_16x16x32_bf16 v[46:49], v[170:173], v[190:193], v[46:49]
	v_mfma_f32_16x16x32_bf16 v[14:17], v[182:185], v[190:193], v[14:17]
	v_mfma_f32_16x16x32_bf16 v[42:45], v[170:173], v[198:201], v[42:45]
	v_mfma_f32_16x16x32_bf16 v[8:11], v[182:185], v[198:201], v[8:11]
	v_mfma_f32_16x16x32_bf16 v[38:41], v[170:173], v[208:211], v[38:41]
	v_mfma_f32_16x16x32_bf16 v[4:7], v[182:185], v[208:211], v[4:7]
	v_mfma_f32_16x16x32_bf16 v[18:21], v[170:173], v[222:225], v[18:21]
	v_mfma_f32_16x16x32_bf16 v[0:3], v[182:185], v[222:225], v[0:3]
	s_setprio 0
	s_barrier
	s_add_i32 s83, s83, 2
	s_add_u32 s8, s8, 0x100
	s_addc_u32 s9, s9, 0
	s_add_u32 s68, s68, 0x100
	s_addc_u32 s69, s69, 0
	s_cmp_gt_u32 s83, 13
	s_cbranch_scc0 .LBB0_916
	s_and_b64 vcc, exec, s[22:23]
	s_cbranch_vccz .LBB0_919
	s_barrier

; #define PG8_STAGE(bufoff, gbase, voff) do { _Pragma("unroll") for (int _i = 0; _i < 2; ++_i) \
;         __builtin_amdgcn_global_load_lds((const unsigned*)((const char*)(gbase) + (voff)[_i]), (LAS unsigned*)(lds + (bufoff) + ldsw + _i * 8192), 16, 0, 0); } while (0)
; #define PG8_LDA(dst, b, h) do { _Pragma("unroll") for (int m = 0; m < 4; ++m) _Pragma("unroll") for (int k = 0; k < 2; ++k) dst[m][k] = *(const LAS bf16x8*)(lds + PG8_SA(b, h) + aoff + m * 2048 + k * 1024); } while (0)
; #define PG8_LDB(dst, b, h) do { _Pragma("unroll") for (int n = 0; n < 2; ++n) _Pragma("unroll") for (int k = 0; k < 2; ++k) dst[n][k] = *(const LAS bf16x8*)(lds + PG8_SB(b, h) + boff + n * 2048 + k * 1024); } while (0)
; #define PG8_MMA(ai, bj, At, Bt) do { __builtin_amdgcn_s_setprio(1); _Pragma("unroll") for (int m = 0; m < 4; ++m) _Pragma("unroll") for (int n = 0; n < 2; ++n) _Pragma("unroll") for (int k = 0; k < 2; ++k) \
;         acc[ai][bj][m][n] = __builtin_amdgcn_mfma_f32_16x16x32_bf16(Bt[n][k], At[m][k], acc[ai][bj][m][n], 0, 0, 0); __builtin_amdgcn_s_setprio(0); } while (0)
; #define PG8_BAR __builtin_amdgcn_s_barrier()
; template <class Epi>
; __device__ __forceinline__ void gemm_phase(LAS unsigned char* lds, const Gemm g, const StaticOrder& S, const Epi& E, int wave_s) {
;     ...
;         const bool has_next = S.next(ui + 1, nxt);
;         const char* nA = has_next ? (const char*)g.A + (size_t)nxt.pm * tstepA : cA; const char* nB = has_next ? (const char*)g.Bt + (size_t)nxt.pn * tstepB : cB;
;         for (int t = 0; t < nt; t += 2) {
;             const bool last = (t == nt - 2);
;             const char* a1 = cA + (size_t)(t + 1) * kstep;
;             const char* a2 = last ? nA : cA + (size_t)(t + 2) * kstep; const char* b2 = last ? nB : cB + (size_t)(t + 2) * kstep;
;             const char* a3 = a2 + kstep; const char* b3 = b2 + kstep;
;             PG8_LDB(B0, 0, 0); PG8_LDB(B1, 0, 1); PG8_SCHED; PG8_LDA(At, 0, 0); PG8_STAGE(PG8_SA(1, 1), a1 + hstepA, voffA);
;             PG8_WAIT_V(8); PG8_WAIT_L(0); PG8_BAR; PG8_MMA(0, 0, At, B0); PG8_MMA(0, 1, At, B1); PG8_BAR; PG8_SCHED;
;             PG8_LDA(At, 0, 1); PG8_STAGE(PG8_SB(0, 0), b2, voffB); PG8_STAGE(PG8_SB(0, 1), b2 + hstepB, voffB); PG8_STAGE(PG8_SA(0, 0), a2, voffA);
;             PG8_WAIT_V(8); PG8_WAIT_L(0); PG8_BAR; PG8_MMA(1, 0, At, B0); PG8_MMA(1, 1, At, B1); PG8_BAR; PG8_SCHED;
.LBB0_1044:
	s_add_u32 s26, s22, 0xfffc0080
	s_addc_u32 s27, s23, -1
	s_add_i32 s53, 0, 0x10000
	s_cmp_eq_u32 s52, 12
	s_cselect_b32 s31, s11, s27
	s_cselect_b32 s30, s48, s26
	v_add_u32_e32 v145, s53, v143
	s_cselect_b32 s27, s9, s51
	s_cselect_b32 s26, s49, s50
	s_add_i32 s54, 0, 0x14000
	ds_read_b128 v[146:149], v145
	ds_read_b128 v[150:153], v145 offset:1024
	ds_read_b128 v[154:157], v145 offset:2048
	ds_read_b128 v[158:161], v145 offset:3072
	v_add_u32_e32 v145, s54, v143
	ds_read_b128 v[182:185], v144
	ds_read_b128 v[186:189], v144 offset:1024
	ds_read_b128 v[190:193], v144 offset:2048
	ds_read_b128 v[194:197], v144 offset:3072
	ds_read_b128 v[198:201], v144 offset:4096
	ds_read_b128 v[202:205], v144 offset:5120
	ds_read_b128 v[206:209], v144 offset:6144
	ds_read_b128 v[210:213], v144 offset:7168
	ds_read_b128 v[162:165], v145
	ds_read_b128 v[166:169], v145 offset:1024
	ds_read_b128 v[170:173], v145 offset:2048
	ds_read_b128 v[178:181], v145 offset:3072
	v_lshl_add_u64 v[174:175], s[22:23], 0, v[138:139]
	s_add_i32 m0, s37, 0xc000
	global_load_lds_dwordx4 v[174:175], off
	v_lshl_add_u64 v[174:175], s[22:23], 0, v[140:141]
	s_add_i32 m0, s37, 0xe000
	s_nop 0
	global_load_lds_dwordx4 v[174:175], off
	s_waitcnt vmcnt(8)
	s_cmp_lg_u64 s[6:7], 0
	s_cbranch_scc1 .Lpp_lead_7
	s_waitcnt lgkmcnt(0)
.Lpp_lead_7:
	s_waitcnt lgkmcnt(4)
	s_barrier
	s_setprio 1
	s_waitcnt lgkmcnt(4)
	v_mfma_f32_16x16x32_bf16 v[126:129], v[146:149], v[182:185], v[126:129]
	v_mfma_f32_16x16x32_bf16 v[122:125], v[154:157], v[182:185], v[122:125]
	v_mfma_f32_16x16x32_bf16 v[118:121], v[146:149], v[190:193], v[118:121]
	v_mfma_f32_16x16x32_bf16 v[114:117], v[154:157], v[190:193], v[114:117]
	v_mfma_f32_16x16x32_bf16 v[102:105], v[146:149], v[198:201], v[102:105]
	v_mfma_f32_16x16x32_bf16 v[98:101], v[154:157], v[198:201], v[98:101]
	v_mfma_f32_16x16x32_bf16 v[86:89], v[146:149], v[206:209], v[86:89]
	v_mfma_f32_16x16x32_bf16 v[82:85], v[154:157], v[206:209], v[82:85]
	v_mfma_f32_16x16x32_bf16 v[126:129], v[150:153], v[186:189], v[126:129]
	v_mfma_f32_16x16x32_bf16 v[122:125], v[158:161], v[186:189], v[122:125]
	v_mfma_f32_16x16x32_bf16 v[118:121], v[150:153], v[194:197], v[118:121]
	v_mfma_f32_16x16x32_bf16 v[114:117], v[158:161], v[194:197], v[114:117]
	v_mfma_f32_16x16x32_bf16 v[102:105], v[150:153], v[202:205], v[102:105]
	v_mfma_f32_16x16x32_bf16 v[98:101], v[158:161], v[202:205], v[98:101]
	v_mfma_f32_16x16x32_bf16 v[86:89], v[150:153], v[210:213], v[86:89]
	v_mfma_f32_16x16x32_bf16 v[82:85], v[158:161], v[210:213], v[82:85]
	s_setprio 0
	s_setprio 1
	s_waitcnt lgkmcnt(0)
	v_mfma_f32_16x16x32_bf16 v[110:113], v[162:165], v[182:185], v[110:113]
	v_mfma_f32_16x16x32_bf16 v[106:109], v[170:173], v[182:185], v[106:109]
	v_mfma_f32_16x16x32_bf16 v[94:97], v[162:165], v[190:193], v[94:97]
	v_mfma_f32_16x16x32_bf16 v[90:93], v[170:173], v[190:193], v[90:93]
	v_mfma_f32_16x16x32_bf16 v[78:81], v[162:165], v[198:201], v[78:81]
	v_mfma_f32_16x16x32_bf16 v[74:77], v[170:173], v[198:201], v[74:77]
	v_mfma_f32_16x16x32_bf16 v[70:73], v[162:165], v[206:209], v[70:73]
	v_mfma_f32_16x16x32_bf16 v[66:69], v[170:173], v[206:209], v[66:69]
	v_mfma_f32_16x16x32_bf16 v[110:113], v[166:169], v[186:189], v[110:113]
	v_mfma_f32_16x16x32_bf16 v[106:109], v[178:181], v[186:189], v[106:109]
	v_mfma_f32_16x16x32_bf16 v[94:97], v[166:169], v[194:197], v[94:97]
	v_mfma_f32_16x16x32_bf16 v[90:93], v[178:181], v[194:197], v[90:93]
	v_mfma_f32_16x16x32_bf16 v[78:81], v[166:169], v[202:205], v[78:81]
	v_mfma_f32_16x16x32_bf16 v[74:77], v[178:181], v[202:205], v[74:77]
	v_mfma_f32_16x16x32_bf16 v[70:73], v[166:169], v[210:213], v[70:73]
	v_mfma_f32_16x16x32_bf16 v[66:69], v[178:181], v[210:213], v[66:69]
	s_setprio 0
	s_barrier
	s_add_i32 s53, s53, s36
	v_lshl_add_u64 v[174:175], s[26:27], 0, v[134:135]
	s_mov_b32 m0, s53
	ds_read_b128 v[182:185], v144 offset:16384
	ds_read_b128 v[186:189], v144 offset:17408
	ds_read_b128 v[190:193], v144 offset:18432
	ds_read_b128 v[194:197], v144 offset:19456
	ds_read_b128 v[198:201], v144 offset:20480
	ds_read_b128 v[202:205], v144 offset:21504
	ds_read_b128 v[206:209], v144 offset:22528
	ds_read_b128 v[210:213], v144 offset:23552
	global_load_lds_dwordx4 v[174:175], off
	s_add_i32 m0, s53, 0x2000
	s_add_u32 s58, s26, 0x40000
	v_lshl_add_u64 v[176:177], s[26:27], 0, v[130:131]
	s_addc_u32 s59, s27, 0
	s_add_i32 s53, s54, s36
	global_load_lds_dwordx4 v[176:177], off
	v_lshl_add_u64 v[214:215], s[58:59], 0, v[134:135]
	s_mov_b32 m0, s53
	v_lshl_add_u64 v[216:217], s[30:31], 0, v[132:133]
	global_load_lds_dwordx4 v[214:215], off
	v_lshl_add_u64 v[214:215], s[58:59], 0, v[130:131]
	s_add_i32 m0, s53, 0x2000
	s_nop 0
	global_load_lds_dwordx4 v[214:215], off
	v_lshl_add_u64 v[214:215], s[30:31], 0, v[136:137]
	s_mov_b32 m0, s37
	s_nop 0
	global_load_lds_dwordx4 v[214:215], off
	s_mov_b32 m0, s40
	s_nop 0
	global_load_lds_dwordx4 v[216:217], off
	s_waitcnt vmcnt(8)
	s_waitcnt lgkmcnt(0)
	s_barrier
; #define PG8_STAGE(bufoff, gbase, voff) do { _Pragma("unroll") for (int _i = 0; _i < 2; ++_i) \
;         __builtin_amdgcn_global_load_lds((const unsigned*)((const char*)(gbase) + (voff)[_i]), (LAS unsigned*)(lds + (bufoff) + ldsw + _i * 8192), 16, 0, 0); } while (0)
; #define PG8_LDA(dst, b, h) do { _Pragma("unroll") for (int m = 0; m < 4; ++m) _Pragma("unroll") for (int k = 0; k < 2; ++k) dst[m][k] = *(const LAS bf16x8*)(lds + PG8_SA(b, h) + aoff + m * 2048 + k * 1024); } while (0)
; #define PG8_LDB(dst, b, h) do { _Pragma("unroll") for (int n = 0; n < 2; ++n) _Pragma("unroll") for (int k = 0; k < 2; ++k) dst[n][k] = *(const LAS bf16x8*)(lds + PG8_SB(b, h) + boff + n * 2048 + k * 1024); } while (0)
; #define PG8_MMA(ai, bj, At, Bt) do { __builtin_amdgcn_s_setprio(1); _Pragma("unroll") for (int m = 0; m < 4; ++m) _Pragma("unroll") for (int n = 0; n < 2; ++n) _Pragma("unroll") for (int k = 0; k < 2; ++k) \
;         acc[ai][bj][m][n] = __builtin_amdgcn_mfma_f32_16x16x32_bf16(Bt[n][k], At[m][k], acc[ai][bj][m][n], 0, 0, 0); __builtin_amdgcn_s_setprio(0); } while (0)
; #define PG8_WAIT_V(n) asm volatile("s_waitcnt vmcnt(" #n ")" ::: "memory")
; #define PG8_WAIT_L(n) asm volatile("s_waitcnt lgkmcnt(" #n ")" ::: "memory")
; #define PG8_BAR __builtin_amdgcn_s_barrier()
; #define PG8_SCHED __builtin_amdgcn_sched_barrier(0)
; template <class Epi>
; __device__ __forceinline__ void gemm_phase(LAS unsigned char* lds, const Gemm g, const StaticOrder& S, const Epi& E, int wave_s) {
;     ...
;             PG8_WAIT_V(8); PG8_WAIT_L(0); PG8_BAR; PG8_MMA(1, 0, At, B0); PG8_MMA(1, 1, At, B1); PG8_BAR; PG8_SCHED;
;             PG8_LDB(B0, 1, 0); PG8_LDB(B1, 1, 1); PG8_SCHED; PG8_LDA(At, 1, 0); PG8_STAGE(PG8_SA(0, 1), a2 + hstepA, voffA);
;             PG8_WAIT_V(8); PG8_WAIT_L(0); PG8_BAR; PG8_MMA(0, 0, At, B0); PG8_MMA(0, 1, At, B1); PG8_BAR; PG8_SCHED;
	s_setprio 1
	s_waitcnt lgkmcnt(0)
	v_mfma_f32_16x16x32_bf16 v[62:65], v[146:149], v[182:185], v[62:65]
	v_mfma_f32_16x16x32_bf16 v[58:61], v[154:157], v[182:185], v[58:61]
	v_mfma_f32_16x16x32_bf16 v[54:57], v[146:149], v[190:193], v[54:57]
	v_mfma_f32_16x16x32_bf16 v[50:53], v[154:157], v[190:193], v[50:53]
	v_mfma_f32_16x16x32_bf16 v[38:41], v[146:149], v[198:201], v[38:41]
	v_mfma_f32_16x16x32_bf16 v[34:37], v[154:157], v[198:201], v[34:37]
	v_mfma_f32_16x16x32_bf16 v[22:25], v[146:149], v[206:209], v[22:25]
	v_mfma_f32_16x16x32_bf16 v[18:21], v[154:157], v[206:209], v[18:21]
	v_mfma_f32_16x16x32_bf16 v[62:65], v[150:153], v[186:189], v[62:65]
	v_mfma_f32_16x16x32_bf16 v[58:61], v[158:161], v[186:189], v[58:61]
	v_mfma_f32_16x16x32_bf16 v[54:57], v[150:153], v[194:197], v[54:57]
	v_mfma_f32_16x16x32_bf16 v[50:53], v[158:161], v[194:197], v[50:53]
	v_mfma_f32_16x16x32_bf16 v[38:41], v[150:153], v[202:205], v[38:41]
	v_mfma_f32_16x16x32_bf16 v[34:37], v[158:161], v[202:205], v[34:37]
	v_mfma_f32_16x16x32_bf16 v[22:25], v[150:153], v[210:213], v[22:25]
	v_mfma_f32_16x16x32_bf16 v[18:21], v[158:161], v[210:213], v[18:21]
	s_setprio 0
	s_setprio 1
	v_mfma_f32_16x16x32_bf16 v[46:49], v[162:165], v[182:185], v[46:49]
	v_mfma_f32_16x16x32_bf16 v[42:45], v[170:173], v[182:185], v[42:45]
	v_mfma_f32_16x16x32_bf16 v[30:33], v[162:165], v[190:193], v[30:33]
	v_mfma_f32_16x16x32_bf16 v[26:29], v[170:173], v[190:193], v[26:29]
	v_mfma_f32_16x16x32_bf16 v[14:17], v[162:165], v[198:201], v[14:17]
	v_mfma_f32_16x16x32_bf16 v[8:11], v[170:173], v[198:201], v[8:11]
	v_mfma_f32_16x16x32_bf16 v[4:7], v[162:165], v[206:209], v[4:7]
	v_mfma_f32_16x16x32_bf16 v[0:3], v[170:173], v[206:209], v[0:3]
	v_mfma_f32_16x16x32_bf16 v[46:49], v[166:169], v[186:189], v[46:49]
	v_mfma_f32_16x16x32_bf16 v[42:45], v[178:181], v[186:189], v[42:45]
	v_mfma_f32_16x16x32_bf16 v[30:33], v[166:169], v[194:197], v[30:33]
	v_mfma_f32_16x16x32_bf16 v[26:29], v[178:181], v[194:197], v[26:29]
	v_mfma_f32_16x16x32_bf16 v[14:17], v[166:169], v[202:205], v[14:17]
	v_mfma_f32_16x16x32_bf16 v[8:11], v[178:181], v[202:205], v[8:11]
	v_mfma_f32_16x16x32_bf16 v[4:7], v[166:169], v[210:213], v[4:7]
	v_mfma_f32_16x16x32_bf16 v[0:3], v[178:181], v[210:213], v[0:3]
	s_setprio 0
	s_barrier
	s_add_i32 s53, 0, 0x18000
	v_add_u32_e32 v145, s53, v143
	s_add_i32 s54, 0, 0x1c000
	ds_read_b128 v[146:149], v145
	ds_read_b128 v[150:153], v145 offset:1024
	ds_read_b128 v[154:157], v145 offset:2048
	ds_read_b128 v[158:161], v145 offset:3072
	v_add_u32_e32 v145, s54, v143
	ds_read_b128 v[182:185], v144 offset:32768
	ds_read_b128 v[186:189], v144 offset:33792
	ds_read_b128 v[190:193], v144 offset:34816
	ds_read_b128 v[194:197], v144 offset:35840
	ds_read_b128 v[198:201], v144 offset:36864
	ds_read_b128 v[202:205], v144 offset:37888
	ds_read_b128 v[206:209], v144 offset:38912
	ds_read_b128 v[210:213], v144 offset:39936
	ds_read_b128 v[162:165], v145
	ds_read_b128 v[166:169], v145 offset:1024
	ds_read_b128 v[170:173], v145 offset:2048
	ds_read_b128 v[178:181], v145 offset:3072
	s_add_u32 s30, s30, 0x40000
	s_addc_u32 s31, s31, 0
	s_mov_b32 m0, s41
	v_lshl_add_u64 v[218:219], s[30:31], 0, v[136:137]
	global_load_lds_dwordx4 v[218:219], off
	v_lshl_add_u64 v[218:219], s[30:31], 0, v[132:133]
	s_mov_b32 m0, s42
	s_nop 0
	global_load_lds_dwordx4 v[218:219], off
	s_waitcnt vmcnt(8)
	s_cmp_lg_u64 s[6:7], 0
	s_cbranch_scc1 .Lpp_lead_8
	s_waitcnt lgkmcnt(0)
; #define PG8_STAGE(bufoff, gbase, voff) do { _Pragma("unroll") for (int _i = 0; _i < 2; ++_i) \
;         __builtin_amdgcn_global_load_lds((const unsigned*)((const char*)(gbase) + (voff)[_i]), (LAS unsigned*)(lds + (bufoff) + ldsw + _i * 8192), 16, 0, 0); } while (0)
; #define PG8_LDA(dst, b, h) do { _Pragma("unroll") for (int m = 0; m < 4; ++m) _Pragma("unroll") for (int k = 0; k < 2; ++k) dst[m][k] = *(const LAS bf16x8*)(lds + PG8_SA(b, h) + aoff + m * 2048 + k * 1024); } while (0)
; #define PG8_MMA(ai, bj, At, Bt) do { __builtin_amdgcn_s_setprio(1); _Pragma("unroll") for (int m = 0; m < 4; ++m) _Pragma("unroll") for (int n = 0; n < 2; ++n) _Pragma("unroll") for (int k = 0; k < 2; ++k) \
;         acc[ai][bj][m][n] = __builtin_amdgcn_mfma_f32_16x16x32_bf16(Bt[n][k], At[m][k], acc[ai][bj][m][n], 0, 0, 0); __builtin_amdgcn_s_setprio(0); } while (0)
; #define PG8_WAIT_V(n) asm volatile("s_waitcnt vmcnt(" #n ")" ::: "memory")
; #define PG8_WAIT_L(n) asm volatile("s_waitcnt lgkmcnt(" #n ")" ::: "memory")
; #define PG8_BAR __builtin_amdgcn_s_barrier()
; #define PG8_SCHED __builtin_amdgcn_sched_barrier(0)
; template <class Epi>
; __device__ __forceinline__ void gemm_phase(LAS unsigned char* lds, const Gemm g, const StaticOrder& S, const Epi& E, int wave_s) {
;     ...
;             PG8_WAIT_V(8); PG8_WAIT_L(0); PG8_BAR; PG8_MMA(0, 0, At, B0); PG8_MMA(0, 1, At, B1); PG8_BAR; PG8_SCHED;
;             PG8_LDA(At, 1, 1); PG8_STAGE(PG8_SB(1, 0), b3, voffB); PG8_STAGE(PG8_SB(1, 1), b3 + hstepB, voffB); PG8_STAGE(PG8_SA(1, 0), a3, voffA);
;             PG8_WAIT_V(8); PG8_WAIT_L(0); PG8_BAR; PG8_MMA(1, 0, At, B0); PG8_MMA(1, 1, At, B1); PG8_BAR; PG8_SCHED;
;         }
;         if (wr == 0) PG8_BAR;
.Lpp_lead_8:
	s_waitcnt lgkmcnt(4)
	s_barrier
	s_setprio 1
	s_waitcnt lgkmcnt(4)
	v_mfma_f32_16x16x32_bf16 v[126:129], v[146:149], v[182:185], v[126:129]
	v_mfma_f32_16x16x32_bf16 v[122:125], v[154:157], v[182:185], v[122:125]
	v_mfma_f32_16x16x32_bf16 v[118:121], v[146:149], v[190:193], v[118:121]
	v_mfma_f32_16x16x32_bf16 v[114:117], v[154:157], v[190:193], v[114:117]
	v_mfma_f32_16x16x32_bf16 v[102:105], v[146:149], v[198:201], v[102:105]
	v_mfma_f32_16x16x32_bf16 v[98:101], v[154:157], v[198:201], v[98:101]
	v_mfma_f32_16x16x32_bf16 v[86:89], v[146:149], v[206:209], v[86:89]
	v_mfma_f32_16x16x32_bf16 v[82:85], v[154:157], v[206:209], v[82:85]
	v_mfma_f32_16x16x32_bf16 v[126:129], v[150:153], v[186:189], v[126:129]
	v_mfma_f32_16x16x32_bf16 v[122:125], v[158:161], v[186:189], v[122:125]
	v_mfma_f32_16x16x32_bf16 v[118:121], v[150:153], v[194:197], v[118:121]
	v_mfma_f32_16x16x32_bf16 v[114:117], v[158:161], v[194:197], v[114:117]
	v_mfma_f32_16x16x32_bf16 v[102:105], v[150:153], v[202:205], v[102:105]
	v_mfma_f32_16x16x32_bf16 v[98:101], v[158:161], v[202:205], v[98:101]
	v_mfma_f32_16x16x32_bf16 v[86:89], v[150:153], v[210:213], v[86:89]
	v_mfma_f32_16x16x32_bf16 v[82:85], v[158:161], v[210:213], v[82:85]
	s_setprio 0
	s_setprio 1
	s_waitcnt lgkmcnt(0)
	v_mfma_f32_16x16x32_bf16 v[110:113], v[162:165], v[182:185], v[110:113]
	v_mfma_f32_16x16x32_bf16 v[106:109], v[170:173], v[182:185], v[106:109]
	v_mfma_f32_16x16x32_bf16 v[94:97], v[162:165], v[190:193], v[94:97]
	v_mfma_f32_16x16x32_bf16 v[90:93], v[170:173], v[190:193], v[90:93]
	v_mfma_f32_16x16x32_bf16 v[78:81], v[162:165], v[198:201], v[78:81]
	v_mfma_f32_16x16x32_bf16 v[74:77], v[170:173], v[198:201], v[74:77]
	v_mfma_f32_16x16x32_bf16 v[70:73], v[162:165], v[206:209], v[70:73]
	v_mfma_f32_16x16x32_bf16 v[66:69], v[170:173], v[206:209], v[66:69]
	v_mfma_f32_16x16x32_bf16 v[110:113], v[166:169], v[186:189], v[110:113]
	v_mfma_f32_16x16x32_bf16 v[106:109], v[178:181], v[186:189], v[106:109]
	v_mfma_f32_16x16x32_bf16 v[94:97], v[166:169], v[194:197], v[94:97]
	v_mfma_f32_16x16x32_bf16 v[90:93], v[178:181], v[194:197], v[90:93]
	v_mfma_f32_16x16x32_bf16 v[78:81], v[166:169], v[202:205], v[78:81]
	v_mfma_f32_16x16x32_bf16 v[74:77], v[178:181], v[202:205], v[74:77]
	v_mfma_f32_16x16x32_bf16 v[70:73], v[166:169], v[210:213], v[70:73]
	v_mfma_f32_16x16x32_bf16 v[66:69], v[178:181], v[210:213], v[66:69]
	s_setprio 0
	s_barrier
	s_add_i32 s30, s53, s36
	v_lshl_add_u64 v[174:175], v[174:175], 0, s[84:85]
	s_mov_b32 m0, s30
	ds_read_b128 v[182:185], v144 offset:49152
	ds_read_b128 v[186:189], v144 offset:50176
	ds_read_b128 v[190:193], v144 offset:51200
	ds_read_b128 v[194:197], v144 offset:52224
	ds_read_b128 v[198:201], v144 offset:53248
	ds_read_b128 v[202:205], v144 offset:54272
	ds_read_b128 v[206:209], v144 offset:55296
	ds_read_b128 v[210:213], v144 offset:56320
	global_load_lds_dwordx4 v[174:175], off
	s_add_i32 m0, s30, 0x2000
	s_add_u32 s26, s26, 0x40080
	v_lshl_add_u64 v[174:175], v[176:177], 0, s[84:85]
	s_addc_u32 s27, s27, 0
	s_add_i32 s30, s54, s36
	global_load_lds_dwordx4 v[174:175], off
	v_lshl_add_u64 v[174:175], s[26:27], 0, v[134:135]
	s_mov_b32 m0, s30
	s_nop 0
	global_load_lds_dwordx4 v[174:175], off
	v_lshl_add_u64 v[174:175], s[26:27], 0, v[130:131]
	s_add_i32 m0, s30, 0x2000
	s_nop 0
	global_load_lds_dwordx4 v[174:175], off
	v_lshl_add_u64 v[174:175], v[214:215], 0, s[84:85]
	s_mov_b32 m0, s43
	s_nop 0
	global_load_lds_dwordx4 v[174:175], off
	v_lshl_add_u64 v[174:175], v[216:217], 0, s[84:85]
	s_mov_b32 m0, s44
	s_nop 0
	global_load_lds_dwordx4 v[174:175], off
	s_waitcnt vmcnt(8)
	s_waitcnt lgkmcnt(0)
	s_barrier
	s_setprio 1
	s_waitcnt lgkmcnt(0)
	v_mfma_f32_16x16x32_bf16 v[62:65], v[146:149], v[182:185], v[62:65]
	v_mfma_f32_16x16x32_bf16 v[58:61], v[154:157], v[182:185], v[58:61]
	v_mfma_f32_16x16x32_bf16 v[54:57], v[146:149], v[190:193], v[54:57]
	v_mfma_f32_16x16x32_bf16 v[50:53], v[154:157], v[190:193], v[50:53]
	v_mfma_f32_16x16x32_bf16 v[38:41], v[146:149], v[198:201], v[38:41]
	v_mfma_f32_16x16x32_bf16 v[34:37], v[154:157], v[198:201], v[34:37]
	v_mfma_f32_16x16x32_bf16 v[22:25], v[146:149], v[206:209], v[22:25]
	v_mfma_f32_16x16x32_bf16 v[18:21], v[154:157], v[206:209], v[18:21]
	v_mfma_f32_16x16x32_bf16 v[62:65], v[150:153], v[186:189], v[62:65]
	v_mfma_f32_16x16x32_bf16 v[58:61], v[158:161], v[186:189], v[58:61]
	v_mfma_f32_16x16x32_bf16 v[54:57], v[150:153], v[194:197], v[54:57]
	v_mfma_f32_16x16x32_bf16 v[50:53], v[158:161], v[194:197], v[50:53]
	v_mfma_f32_16x16x32_bf16 v[38:41], v[150:153], v[202:205], v[38:41]
	v_mfma_f32_16x16x32_bf16 v[34:37], v[158:161], v[202:205], v[34:37]
	v_mfma_f32_16x16x32_bf16 v[22:25], v[150:153], v[210:213], v[22:25]
	v_mfma_f32_16x16x32_bf16 v[18:21], v[158:161], v[210:213], v[18:21]
	s_setprio 0
	s_setprio 1
	v_mfma_f32_16x16x32_bf16 v[46:49], v[162:165], v[182:185], v[46:49]
	v_mfma_f32_16x16x32_bf16 v[42:45], v[170:173], v[182:185], v[42:45]
	v_mfma_f32_16x16x32_bf16 v[30:33], v[162:165], v[190:193], v[30:33]
	v_mfma_f32_16x16x32_bf16 v[26:29], v[170:173], v[190:193], v[26:29]
	v_mfma_f32_16x16x32_bf16 v[14:17], v[162:165], v[198:201], v[14:17]
	v_mfma_f32_16x16x32_bf16 v[8:11], v[170:173], v[198:201], v[8:11]
	v_mfma_f32_16x16x32_bf16 v[4:7], v[162:165], v[206:209], v[4:7]
	v_mfma_f32_16x16x32_bf16 v[0:3], v[170:173], v[206:209], v[0:3]
	v_mfma_f32_16x16x32_bf16 v[46:49], v[166:169], v[186:189], v[46:49]
	v_mfma_f32_16x16x32_bf16 v[42:45], v[178:181], v[186:189], v[42:45]
	v_mfma_f32_16x16x32_bf16 v[30:33], v[166:169], v[194:197], v[30:33]
	v_mfma_f32_16x16x32_bf16 v[26:29], v[178:181], v[194:197], v[26:29]
	v_mfma_f32_16x16x32_bf16 v[14:17], v[166:169], v[202:205], v[14:17]
	v_mfma_f32_16x16x32_bf16 v[8:11], v[178:181], v[202:205], v[8:11]
	v_mfma_f32_16x16x32_bf16 v[4:7], v[166:169], v[210:213], v[4:7]
	v_mfma_f32_16x16x32_bf16 v[0:3], v[178:181], v[210:213], v[0:3]
	s_setprio 0
	s_barrier
	s_add_i32 s52, s52, 2
	s_add_u32 s22, s22, 0x100
	s_addc_u32 s23, s23, 0
	s_add_u32 s50, s50, 0x100
	s_addc_u32 s51, s51, 0
	s_cmp_gt_u32 s52, 13
	s_cbranch_scc0 .LBB0_1044
	s_and_b64 vcc, exec, s[6:7]
	s_cbranch_vccz .LBB0_1047
	s_barrier

; #define PG8_STAGE(bufoff, gbase, voff) do { _Pragma("unroll") for (int _i = 0; _i < 2; ++_i) \
;         __builtin_amdgcn_global_load_lds((const unsigned*)((const char*)(gbase) + (voff)[_i]), (LAS unsigned*)(lds + (bufoff) + ldsw + _i * 8192), 16, 0, 0); } while (0)
; #define PG8_LDA(dst, b, h) do { _Pragma("unroll") for (int m = 0; m < 4; ++m) _Pragma("unroll") for (int k = 0; k < 2; ++k) dst[m][k] = *(const LAS bf16x8*)(lds + PG8_SA(b, h) + aoff + m * 2048 + k * 1024); } while (0)
; #define PG8_LDB(dst, b, h) do { _Pragma("unroll") for (int n = 0; n < 2; ++n) _Pragma("unroll") for (int k = 0; k < 2; ++k) dst[n][k] = *(const LAS bf16x8*)(lds + PG8_SB(b, h) + boff + n * 2048 + k * 1024); } while (0)
; #define PG8_MMA(ai, bj, At, Bt) do { __builtin_amdgcn_s_setprio(1); _Pragma("unroll") for (int m = 0; m < 4; ++m) _Pragma("unroll") for (int n = 0; n < 2; ++n) _Pragma("unroll") for (int k = 0; k < 2; ++k) \
;         acc[ai][bj][m][n] = __builtin_amdgcn_mfma_f32_16x16x32_bf16(Bt[n][k], At[m][k], acc[ai][bj][m][n], 0, 0, 0); __builtin_amdgcn_s_setprio(0); } while (0)
; #define PG8_WAIT_V(n) asm volatile("s_waitcnt vmcnt(" #n ")" ::: "memory")
; #define PG8_WAIT_L(n) asm volatile("s_waitcnt lgkmcnt(" #n ")" ::: "memory")
; #define PG8_BAR __builtin_amdgcn_s_barrier()
; #define PG8_SCHED __builtin_amdgcn_sched_barrier(0)
; template <class Epi>
; __device__ __forceinline__ void gemm_phase(LAS unsigned char* lds, const Gemm g, const StaticOrder& S, const Epi& E, int wave_s) {
;     ...
;         for (int t = 0; t < nt; t += 2) {
;             const bool last = (t == nt - 2);
;             const char* a1 = cA + (size_t)(t + 1) * kstep;
;             const char* a2 = last ? nA : cA + (size_t)(t + 2) * kstep; const char* b2 = last ? nB : cB + (size_t)(t + 2) * kstep;
;             const char* a3 = a2 + kstep; const char* b3 = b2 + kstep;
;             PG8_LDB(B0, 0, 0); PG8_LDB(B1, 0, 1); PG8_SCHED; PG8_LDA(At, 0, 0); PG8_STAGE(PG8_SA(1, 1), a1 + hstepA, voffA);
;             PG8_WAIT_V(8); PG8_WAIT_L(0); PG8_BAR; PG8_MMA(0, 0, At, B0); PG8_MMA(0, 1, At, B1); PG8_BAR; PG8_SCHED;
;             PG8_LDA(At, 0, 1); PG8_STAGE(PG8_SB(0, 0), b2, voffB); PG8_STAGE(PG8_SB(0, 1), b2 + hstepB, voffB); PG8_STAGE(PG8_SA(0, 0), a2, voffA);
;             PG8_WAIT_V(8); PG8_WAIT_L(0); PG8_BAR; PG8_MMA(1, 0, At, B0); PG8_MMA(1, 1, At, B1); PG8_BAR; PG8_SCHED;
.LBB0_1112:
	s_add_u32 s6, s4, 0xfffc0080
	s_addc_u32 s7, s5, -1
	s_add_i32 s47, 0, 0x10000
	s_cmp_eq_u32 s46, 12
	s_cselect_b32 s9, s18, s7
	s_cselect_b32 s8, s35, s6
	v_add_u32_e32 v12, s47, v243
	s_cselect_b32 s7, s36, s45
	s_cselect_b32 s6, s37, s44
	s_add_i32 s50, 0, 0x14000
	ds_read_b128 v[122:125], v12
	ds_read_b128 v[126:129], v12 offset:1024
	ds_read_b128 v[130:133], v12 offset:2048
	ds_read_b128 v[134:137], v12 offset:3072
	v_add_u32_e32 v12, s50, v243
	ds_read_b128 v[162:165], v245
	ds_read_b128 v[166:169], v245 offset:1024
	ds_read_b128 v[170:173], v245 offset:2048
	ds_read_b128 v[190:193], v245 offset:3072
	ds_read_b128 v[194:197], v245 offset:4096
	ds_read_b128 v[198:201], v245 offset:5120
	ds_read_b128 v[202:205], v245 offset:6144
	ds_read_b128 v[206:209], v245 offset:7168
	ds_read_b128 v[138:141], v12
	ds_read_b128 v[142:145], v12 offset:1024
	ds_read_b128 v[146:149], v12 offset:2048
	ds_read_b128 v[150:153], v12 offset:3072
	v_lshl_add_u64 v[174:175], s[4:5], 0, v[186:187]
	s_add_i32 m0, s42, 0xc000
	global_load_lds_dwordx4 v[174:175], off
	v_lshl_add_u64 v[174:175], s[4:5], 0, v[188:189]
	s_add_i32 m0, s42, 0xe000
	s_nop 0
	global_load_lds_dwordx4 v[174:175], off
	s_waitcnt vmcnt(8)
	s_cmp_lg_u64 s[0:1], 0
	s_cbranch_scc1 .Lpp_lead_9
	s_waitcnt lgkmcnt(0)
.Lpp_lead_9:
	s_waitcnt lgkmcnt(4)
	s_barrier
	s_setprio 1
	s_waitcnt lgkmcnt(4)
	v_mfma_f32_16x16x32_bf16 v[158:161], v[122:125], v[162:165], v[158:161]
	v_mfma_f32_16x16x32_bf16 v[154:157], v[130:133], v[162:165], v[154:157]
	v_mfma_f32_16x16x32_bf16 v[118:121], v[122:125], v[170:173], v[118:121]
	v_mfma_f32_16x16x32_bf16 v[114:117], v[130:133], v[170:173], v[114:117]
	v_mfma_f32_16x16x32_bf16 v[110:113], v[122:125], v[194:197], v[110:113]
	v_mfma_f32_16x16x32_bf16 v[106:109], v[130:133], v[194:197], v[106:109]
	v_mfma_f32_16x16x32_bf16 v[102:105], v[122:125], v[202:205], v[102:105]
	v_mfma_f32_16x16x32_bf16 v[98:101], v[130:133], v[202:205], v[98:101]
	v_mfma_f32_16x16x32_bf16 v[158:161], v[126:129], v[166:169], v[158:161]
	v_mfma_f32_16x16x32_bf16 v[154:157], v[134:137], v[166:169], v[154:157]
	v_mfma_f32_16x16x32_bf16 v[118:121], v[126:129], v[190:193], v[118:121]
	v_mfma_f32_16x16x32_bf16 v[114:117], v[134:137], v[190:193], v[114:117]
	v_mfma_f32_16x16x32_bf16 v[110:113], v[126:129], v[198:201], v[110:113]
	v_mfma_f32_16x16x32_bf16 v[106:109], v[134:137], v[198:201], v[106:109]
	v_mfma_f32_16x16x32_bf16 v[102:105], v[126:129], v[206:209], v[102:105]
	v_mfma_f32_16x16x32_bf16 v[98:101], v[134:137], v[206:209], v[98:101]
	s_setprio 0
	s_setprio 1
	s_waitcnt lgkmcnt(0)
	v_mfma_f32_16x16x32_bf16 v[94:97], v[138:141], v[162:165], v[94:97]
	v_mfma_f32_16x16x32_bf16 v[90:93], v[146:149], v[162:165], v[90:93]
	v_mfma_f32_16x16x32_bf16 v[86:89], v[138:141], v[170:173], v[86:89]
	v_mfma_f32_16x16x32_bf16 v[82:85], v[146:149], v[170:173], v[82:85]
	v_mfma_f32_16x16x32_bf16 v[78:81], v[138:141], v[194:197], v[78:81]
	v_mfma_f32_16x16x32_bf16 v[74:77], v[146:149], v[194:197], v[74:77]
	v_mfma_f32_16x16x32_bf16 v[38:41], v[138:141], v[202:205], v[38:41]
	v_mfma_f32_16x16x32_bf16 v[34:37], v[146:149], v[202:205], v[34:37]
	v_mfma_f32_16x16x32_bf16 v[94:97], v[142:145], v[166:169], v[94:97]
	v_mfma_f32_16x16x32_bf16 v[90:93], v[150:153], v[166:169], v[90:93]
	v_mfma_f32_16x16x32_bf16 v[86:89], v[142:145], v[190:193], v[86:89]
	v_mfma_f32_16x16x32_bf16 v[82:85], v[150:153], v[190:193], v[82:85]
	v_mfma_f32_16x16x32_bf16 v[78:81], v[142:145], v[198:201], v[78:81]
	v_mfma_f32_16x16x32_bf16 v[74:77], v[150:153], v[198:201], v[74:77]
	v_mfma_f32_16x16x32_bf16 v[38:41], v[142:145], v[206:209], v[38:41]
	v_mfma_f32_16x16x32_bf16 v[34:37], v[150:153], v[206:209], v[34:37]
	s_setprio 0
	s_barrier
	s_add_i32 s47, s47, s20
	v_lshl_add_u64 v[174:175], s[6:7], 0, v[182:183]
	s_mov_b32 m0, s47
	ds_read_b128 v[162:165], v245 offset:16384
	ds_read_b128 v[166:169], v245 offset:17408
	ds_read_b128 v[170:173], v245 offset:18432
	ds_read_b128 v[190:193], v245 offset:19456
	ds_read_b128 v[194:197], v245 offset:20480
	ds_read_b128 v[198:201], v245 offset:21504
	ds_read_b128 v[202:205], v245 offset:22528
	ds_read_b128 v[206:209], v245 offset:23552
	global_load_lds_dwordx4 v[174:175], off
	s_add_i32 m0, s47, 0x2000
	s_add_u32 s48, s6, 0x40000
	v_lshl_add_u64 v[176:177], s[6:7], 0, v[178:179]
	s_addc_u32 s49, s7, 0
	s_add_i32 s47, s50, s20
	global_load_lds_dwordx4 v[176:177], off
	v_lshl_add_u64 v[210:211], s[48:49], 0, v[182:183]
	s_mov_b32 m0, s47
	v_lshl_add_u64 v[212:213], s[8:9], 0, v[180:181]
	global_load_lds_dwordx4 v[210:211], off
	v_lshl_add_u64 v[210:211], s[48:49], 0, v[178:179]
	s_add_i32 m0, s47, 0x2000
	s_nop 0
	global_load_lds_dwordx4 v[210:211], off
	v_lshl_add_u64 v[210:211], s[8:9], 0, v[184:185]
	s_mov_b32 m0, s42
	s_nop 0
	global_load_lds_dwordx4 v[210:211], off
	s_mov_b32 m0, s43
	s_nop 0
	global_load_lds_dwordx4 v[212:213], off
	s_waitcnt vmcnt(8)
	s_waitcnt lgkmcnt(0)
	s_barrier
; #define PG8_STAGE(bufoff, gbase, voff) do { _Pragma("unroll") for (int _i = 0; _i < 2; ++_i) \
;         __builtin_amdgcn_global_load_lds((const unsigned*)((const char*)(gbase) + (voff)[_i]), (LAS unsigned*)(lds + (bufoff) + ldsw + _i * 8192), 16, 0, 0); } while (0)
; #define PG8_LDA(dst, b, h) do { _Pragma("unroll") for (int m = 0; m < 4; ++m) _Pragma("unroll") for (int k = 0; k < 2; ++k) dst[m][k] = *(const LAS bf16x8*)(lds + PG8_SA(b, h) + aoff + m * 2048 + k * 1024); } while (0)
; #define PG8_LDB(dst, b, h) do { _Pragma("unroll") for (int n = 0; n < 2; ++n) _Pragma("unroll") for (int k = 0; k < 2; ++k) dst[n][k] = *(const LAS bf16x8*)(lds + PG8_SB(b, h) + boff + n * 2048 + k * 1024); } while (0)
; #define PG8_MMA(ai, bj, At, Bt) do { __builtin_amdgcn_s_setprio(1); _Pragma("unroll") for (int m = 0; m < 4; ++m) _Pragma("unroll") for (int n = 0; n < 2; ++n) _Pragma("unroll") for (int k = 0; k < 2; ++k) \
;         acc[ai][bj][m][n] = __builtin_amdgcn_mfma_f32_16x16x32_bf16(Bt[n][k], At[m][k], acc[ai][bj][m][n], 0, 0, 0); __builtin_amdgcn_s_setprio(0); } while (0)
; #define PG8_WAIT_V(n) asm volatile("s_waitcnt vmcnt(" #n ")" ::: "memory")
; #define PG8_WAIT_L(n) asm volatile("s_waitcnt lgkmcnt(" #n ")" ::: "memory")
; #define PG8_BAR __builtin_amdgcn_s_barrier()
; #define PG8_SCHED __builtin_amdgcn_sched_barrier(0)
; template <class Epi>
; __device__ __forceinline__ void gemm_phase(LAS unsigned char* lds, const Gemm g, const StaticOrder& S, const Epi& E, int wave_s) {
;     ...
;             PG8_WAIT_V(8); PG8_WAIT_L(0); PG8_BAR; PG8_MMA(1, 0, At, B0); PG8_MMA(1, 1, At, B1); PG8_BAR; PG8_SCHED;
;             PG8_LDB(B0, 1, 0); PG8_LDB(B1, 1, 1); PG8_SCHED; PG8_LDA(At, 1, 0); PG8_STAGE(PG8_SA(0, 1), a2 + hstepA, voffA);
;             PG8_WAIT_V(8); PG8_WAIT_L(0); PG8_BAR; PG8_MMA(0, 0, At, B0); PG8_MMA(0, 1, At, B1); PG8_BAR; PG8_SCHED;
	s_setprio 1
	s_waitcnt lgkmcnt(0)
	v_mfma_f32_16x16x32_bf16 v[70:73], v[122:125], v[162:165], v[70:73]
	v_mfma_f32_16x16x32_bf16 v[66:69], v[130:133], v[162:165], v[66:69]
	v_mfma_f32_16x16x32_bf16 v[62:65], v[122:125], v[170:173], v[62:65]
	v_mfma_f32_16x16x32_bf16 v[58:61], v[130:133], v[170:173], v[58:61]
	v_mfma_f32_16x16x32_bf16 v[54:57], v[122:125], v[194:197], v[54:57]
	v_mfma_f32_16x16x32_bf16 v[50:53], v[130:133], v[194:197], v[50:53]
	v_mfma_f32_16x16x32_bf16 v[46:49], v[122:125], v[202:205], v[46:49]
	v_mfma_f32_16x16x32_bf16 v[42:45], v[130:133], v[202:205], v[42:45]
	v_mfma_f32_16x16x32_bf16 v[70:73], v[126:129], v[166:169], v[70:73]
	v_mfma_f32_16x16x32_bf16 v[66:69], v[134:137], v[166:169], v[66:69]
	v_mfma_f32_16x16x32_bf16 v[62:65], v[126:129], v[190:193], v[62:65]
	v_mfma_f32_16x16x32_bf16 v[58:61], v[134:137], v[190:193], v[58:61]
	v_mfma_f32_16x16x32_bf16 v[54:57], v[126:129], v[198:201], v[54:57]
	v_mfma_f32_16x16x32_bf16 v[50:53], v[134:137], v[198:201], v[50:53]
	v_mfma_f32_16x16x32_bf16 v[46:49], v[126:129], v[206:209], v[46:49]
	v_mfma_f32_16x16x32_bf16 v[42:45], v[134:137], v[206:209], v[42:45]
	s_setprio 0
	s_setprio 1
	v_mfma_f32_16x16x32_bf16 v[30:33], v[138:141], v[162:165], v[30:33]
	v_mfma_f32_16x16x32_bf16 v[26:29], v[146:149], v[162:165], v[26:29]
	v_mfma_f32_16x16x32_bf16 v[22:25], v[138:141], v[170:173], v[22:25]
	v_mfma_f32_16x16x32_bf16 v[18:21], v[146:149], v[170:173], v[18:21]
	v_mfma_f32_16x16x32_bf16 v[14:17], v[138:141], v[194:197], v[14:17]
	v_mfma_f32_16x16x32_bf16 v[8:11], v[146:149], v[194:197], v[8:11]
	v_mfma_f32_16x16x32_bf16 v[4:7], v[138:141], v[202:205], v[4:7]
	v_mfma_f32_16x16x32_bf16 v[0:3], v[146:149], v[202:205], v[0:3]
	v_mfma_f32_16x16x32_bf16 v[30:33], v[142:145], v[166:169], v[30:33]
	v_mfma_f32_16x16x32_bf16 v[26:29], v[150:153], v[166:169], v[26:29]
	v_mfma_f32_16x16x32_bf16 v[22:25], v[142:145], v[190:193], v[22:25]
	v_mfma_f32_16x16x32_bf16 v[18:21], v[150:153], v[190:193], v[18:21]
	v_mfma_f32_16x16x32_bf16 v[14:17], v[142:145], v[198:201], v[14:17]
	v_mfma_f32_16x16x32_bf16 v[8:11], v[150:153], v[198:201], v[8:11]
	v_mfma_f32_16x16x32_bf16 v[4:7], v[142:145], v[206:209], v[4:7]
	v_mfma_f32_16x16x32_bf16 v[0:3], v[150:153], v[206:209], v[0:3]
	s_setprio 0
	s_barrier
	s_add_i32 s47, 0, 0x18000
	v_add_u32_e32 v12, s47, v243
	s_add_i32 s48, 0, 0x1c000
	ds_read_b128 v[122:125], v12
	ds_read_b128 v[126:129], v12 offset:1024
	ds_read_b128 v[130:133], v12 offset:2048
	ds_read_b128 v[134:137], v12 offset:3072
	v_add_u32_e32 v12, s48, v243
	ds_read_b128 v[162:165], v245 offset:32768
	ds_read_b128 v[166:169], v245 offset:33792
	ds_read_b128 v[170:173], v245 offset:34816
	ds_read_b128 v[190:193], v245 offset:35840
	ds_read_b128 v[194:197], v245 offset:36864
	ds_read_b128 v[198:201], v245 offset:37888
	ds_read_b128 v[202:205], v245 offset:38912
	ds_read_b128 v[206:209], v245 offset:39936
	ds_read_b128 v[138:141], v12
	ds_read_b128 v[142:145], v12 offset:1024
	ds_read_b128 v[146:149], v12 offset:2048
	ds_read_b128 v[150:153], v12 offset:3072
	s_add_u32 s8, s8, 0x40000
	s_addc_u32 s9, s9, 0
	s_mov_b32 m0, s82
	v_lshl_add_u64 v[214:215], s[8:9], 0, v[184:185]
	global_load_lds_dwordx4 v[214:215], off
	v_lshl_add_u64 v[214:215], s[8:9], 0, v[180:181]
	s_mov_b32 m0, s83
	s_nop 0
	global_load_lds_dwordx4 v[214:215], off
	s_waitcnt vmcnt(8)
	s_cmp_lg_u64 s[0:1], 0
	s_cbranch_scc1 .Lpp_lead_10
	s_waitcnt lgkmcnt(0)
; #define PG8_STAGE(bufoff, gbase, voff) do { _Pragma("unroll") for (int _i = 0; _i < 2; ++_i) \
;         __builtin_amdgcn_global_load_lds((const unsigned*)((const char*)(gbase) + (voff)[_i]), (LAS unsigned*)(lds + (bufoff) + ldsw + _i * 8192), 16, 0, 0); } while (0)
; #define PG8_LDA(dst, b, h) do { _Pragma("unroll") for (int m = 0; m < 4; ++m) _Pragma("unroll") for (int k = 0; k < 2; ++k) dst[m][k] = *(const LAS bf16x8*)(lds + PG8_SA(b, h) + aoff + m * 2048 + k * 1024); } while (0)
; #define PG8_MMA(ai, bj, At, Bt) do { __builtin_amdgcn_s_setprio(1); _Pragma("unroll") for (int m = 0; m < 4; ++m) _Pragma("unroll") for (int n = 0; n < 2; ++n) _Pragma("unroll") for (int k = 0; k < 2; ++k) \
;         acc[ai][bj][m][n] = __builtin_amdgcn_mfma_f32_16x16x32_bf16(Bt[n][k], At[m][k], acc[ai][bj][m][n], 0, 0, 0); __builtin_amdgcn_s_setprio(0); } while (0)
; #define PG8_WAIT_V(n) asm volatile("s_waitcnt vmcnt(" #n ")" ::: "memory")
; #define PG8_WAIT_L(n) asm volatile("s_waitcnt lgkmcnt(" #n ")" ::: "memory")
; #define PG8_BAR __builtin_amdgcn_s_barrier()
; #define PG8_SCHED __builtin_amdgcn_sched_barrier(0)
; template <class Epi>
; __device__ __forceinline__ void gemm_phase(LAS unsigned char* lds, const Gemm g, const StaticOrder& S, const Epi& E, int wave_s) {
;     ...
;             PG8_WAIT_V(8); PG8_WAIT_L(0); PG8_BAR; PG8_MMA(0, 0, At, B0); PG8_MMA(0, 1, At, B1); PG8_BAR; PG8_SCHED;
;             PG8_LDA(At, 1, 1); PG8_STAGE(PG8_SB(1, 0), b3, voffB); PG8_STAGE(PG8_SB(1, 1), b3 + hstepB, voffB); PG8_STAGE(PG8_SA(1, 0), a3, voffA);
;             PG8_WAIT_V(8); PG8_WAIT_L(0); PG8_BAR; PG8_MMA(1, 0, At, B0); PG8_MMA(1, 1, At, B1); PG8_BAR; PG8_SCHED;
;         }
;         if (wr == 0) PG8_BAR;
.Lpp_lead_10:
	s_waitcnt lgkmcnt(4)
	s_barrier
	s_setprio 1
	s_waitcnt lgkmcnt(4)
	v_mfma_f32_16x16x32_bf16 v[158:161], v[122:125], v[162:165], v[158:161]
	v_mfma_f32_16x16x32_bf16 v[154:157], v[130:133], v[162:165], v[154:157]
	v_mfma_f32_16x16x32_bf16 v[118:121], v[122:125], v[170:173], v[118:121]
	v_mfma_f32_16x16x32_bf16 v[114:117], v[130:133], v[170:173], v[114:117]
	v_mfma_f32_16x16x32_bf16 v[110:113], v[122:125], v[194:197], v[110:113]
	v_mfma_f32_16x16x32_bf16 v[106:109], v[130:133], v[194:197], v[106:109]
	v_mfma_f32_16x16x32_bf16 v[102:105], v[122:125], v[202:205], v[102:105]
	v_mfma_f32_16x16x32_bf16 v[98:101], v[130:133], v[202:205], v[98:101]
	v_mfma_f32_16x16x32_bf16 v[158:161], v[126:129], v[166:169], v[158:161]
	v_mfma_f32_16x16x32_bf16 v[154:157], v[134:137], v[166:169], v[154:157]
	v_mfma_f32_16x16x32_bf16 v[118:121], v[126:129], v[190:193], v[118:121]
	v_mfma_f32_16x16x32_bf16 v[114:117], v[134:137], v[190:193], v[114:117]
	v_mfma_f32_16x16x32_bf16 v[110:113], v[126:129], v[198:201], v[110:113]
	v_mfma_f32_16x16x32_bf16 v[106:109], v[134:137], v[198:201], v[106:109]
	v_mfma_f32_16x16x32_bf16 v[102:105], v[126:129], v[206:209], v[102:105]
	v_mfma_f32_16x16x32_bf16 v[98:101], v[134:137], v[206:209], v[98:101]
	s_setprio 0
	s_setprio 1
	s_waitcnt lgkmcnt(0)
	v_mfma_f32_16x16x32_bf16 v[94:97], v[138:141], v[162:165], v[94:97]
	v_mfma_f32_16x16x32_bf16 v[90:93], v[146:149], v[162:165], v[90:93]
	v_mfma_f32_16x16x32_bf16 v[86:89], v[138:141], v[170:173], v[86:89]
	v_mfma_f32_16x16x32_bf16 v[82:85], v[146:149], v[170:173], v[82:85]
	v_mfma_f32_16x16x32_bf16 v[78:81], v[138:141], v[194:197], v[78:81]
	v_mfma_f32_16x16x32_bf16 v[74:77], v[146:149], v[194:197], v[74:77]
	v_mfma_f32_16x16x32_bf16 v[38:41], v[138:141], v[202:205], v[38:41]
	v_mfma_f32_16x16x32_bf16 v[34:37], v[146:149], v[202:205], v[34:37]
	v_mfma_f32_16x16x32_bf16 v[94:97], v[142:145], v[166:169], v[94:97]
	v_mfma_f32_16x16x32_bf16 v[90:93], v[150:153], v[166:169], v[90:93]
	v_mfma_f32_16x16x32_bf16 v[86:89], v[142:145], v[190:193], v[86:89]
	v_mfma_f32_16x16x32_bf16 v[82:85], v[150:153], v[190:193], v[82:85]
	v_mfma_f32_16x16x32_bf16 v[78:81], v[142:145], v[198:201], v[78:81]
	v_mfma_f32_16x16x32_bf16 v[74:77], v[150:153], v[198:201], v[74:77]
	v_mfma_f32_16x16x32_bf16 v[38:41], v[142:145], v[206:209], v[38:41]
	v_mfma_f32_16x16x32_bf16 v[34:37], v[150:153], v[206:209], v[34:37]
	s_setprio 0
	s_barrier
	s_add_i32 s8, s47, s20
	v_lshl_add_u64 v[174:175], v[174:175], 0, s[84:85]
	s_mov_b32 m0, s8
	ds_read_b128 v[162:165], v245 offset:49152
	ds_read_b128 v[166:169], v245 offset:50176
	ds_read_b128 v[170:173], v245 offset:51200
	ds_read_b128 v[190:193], v245 offset:52224
	ds_read_b128 v[194:197], v245 offset:53248
	ds_read_b128 v[198:201], v245 offset:54272
	ds_read_b128 v[202:205], v245 offset:55296
	ds_read_b128 v[206:209], v245 offset:56320
	global_load_lds_dwordx4 v[174:175], off
	s_add_i32 m0, s8, 0x2000
	s_add_u32 s6, s6, 0x40080
	v_lshl_add_u64 v[174:175], v[176:177], 0, s[84:85]
	s_addc_u32 s7, s7, 0
	s_add_i32 s8, s48, s20
	global_load_lds_dwordx4 v[174:175], off
	v_lshl_add_u64 v[174:175], s[6:7], 0, v[182:183]
	s_mov_b32 m0, s8
	s_nop 0
	global_load_lds_dwordx4 v[174:175], off
	v_lshl_add_u64 v[174:175], s[6:7], 0, v[178:179]
	s_add_i32 m0, s8, 0x2000
	s_nop 0
	global_load_lds_dwordx4 v[174:175], off
	v_lshl_add_u64 v[174:175], v[210:211], 0, s[84:85]
	s_mov_b32 m0, s96
	s_nop 0
	global_load_lds_dwordx4 v[174:175], off
	v_lshl_add_u64 v[174:175], v[212:213], 0, s[84:85]
	s_mov_b32 m0, s97
	s_nop 0
	global_load_lds_dwordx4 v[174:175], off
	s_waitcnt vmcnt(8)
	s_waitcnt lgkmcnt(0)
	s_barrier
	s_setprio 1
	s_waitcnt lgkmcnt(0)
	v_mfma_f32_16x16x32_bf16 v[70:73], v[122:125], v[162:165], v[70:73]
	v_mfma_f32_16x16x32_bf16 v[66:69], v[130:133], v[162:165], v[66:69]
	v_mfma_f32_16x16x32_bf16 v[62:65], v[122:125], v[170:173], v[62:65]
	v_mfma_f32_16x16x32_bf16 v[58:61], v[130:133], v[170:173], v[58:61]
	v_mfma_f32_16x16x32_bf16 v[54:57], v[122:125], v[194:197], v[54:57]
	v_mfma_f32_16x16x32_bf16 v[50:53], v[130:133], v[194:197], v[50:53]
	v_mfma_f32_16x16x32_bf16 v[46:49], v[122:125], v[202:205], v[46:49]
	v_mfma_f32_16x16x32_bf16 v[42:45], v[130:133], v[202:205], v[42:45]
	v_mfma_f32_16x16x32_bf16 v[70:73], v[126:129], v[166:169], v[70:73]
	v_mfma_f32_16x16x32_bf16 v[66:69], v[134:137], v[166:169], v[66:69]
	v_mfma_f32_16x16x32_bf16 v[62:65], v[126:129], v[190:193], v[62:65]
	v_mfma_f32_16x16x32_bf16 v[58:61], v[134:137], v[190:193], v[58:61]
	v_mfma_f32_16x16x32_bf16 v[54:57], v[126:129], v[198:201], v[54:57]
	v_mfma_f32_16x16x32_bf16 v[50:53], v[134:137], v[198:201], v[50:53]
	v_mfma_f32_16x16x32_bf16 v[46:49], v[126:129], v[206:209], v[46:49]
	v_mfma_f32_16x16x32_bf16 v[42:45], v[134:137], v[206:209], v[42:45]
	s_setprio 0
	s_setprio 1
	v_mfma_f32_16x16x32_bf16 v[30:33], v[138:141], v[162:165], v[30:33]
	v_mfma_f32_16x16x32_bf16 v[26:29], v[146:149], v[162:165], v[26:29]
	v_mfma_f32_16x16x32_bf16 v[22:25], v[138:141], v[170:173], v[22:25]
	v_mfma_f32_16x16x32_bf16 v[18:21], v[146:149], v[170:173], v[18:21]
	v_mfma_f32_16x16x32_bf16 v[14:17], v[138:141], v[194:197], v[14:17]
	v_mfma_f32_16x16x32_bf16 v[8:11], v[146:149], v[194:197], v[8:11]
	v_mfma_f32_16x16x32_bf16 v[4:7], v[138:141], v[202:205], v[4:7]
	v_mfma_f32_16x16x32_bf16 v[0:3], v[146:149], v[202:205], v[0:3]
	v_mfma_f32_16x16x32_bf16 v[30:33], v[142:145], v[166:169], v[30:33]
	v_mfma_f32_16x16x32_bf16 v[26:29], v[150:153], v[166:169], v[26:29]
	v_mfma_f32_16x16x32_bf16 v[22:25], v[142:145], v[190:193], v[22:25]
	v_mfma_f32_16x16x32_bf16 v[18:21], v[150:153], v[190:193], v[18:21]
	v_mfma_f32_16x16x32_bf16 v[14:17], v[142:145], v[198:201], v[14:17]
	v_mfma_f32_16x16x32_bf16 v[8:11], v[150:153], v[198:201], v[8:11]
	v_mfma_f32_16x16x32_bf16 v[4:7], v[142:145], v[206:209], v[4:7]
	v_mfma_f32_16x16x32_bf16 v[0:3], v[150:153], v[206:209], v[0:3]
	s_setprio 0
	s_barrier
	s_add_i32 s46, s46, 2
	s_add_u32 s4, s4, 0x100
	s_addc_u32 s5, s5, 0
	s_add_u32 s44, s44, 0x100
	s_addc_u32 s45, s45, 0
	s_cmp_gt_u32 s46, 13
	s_cbranch_scc0 .LBB0_1112
	s_and_b64 vcc, exec, s[0:1]
	s_cbranch_vccz .LBB0_1115
	s_barrier

; #define PG8_STAGE(bufoff, gbase, voff) do { _Pragma("unroll") for (int _i = 0; _i < 2; ++_i) \
;         __builtin_amdgcn_global_load_lds((const unsigned*)((const char*)(gbase) + (voff)[_i]), (LAS unsigned*)(lds + (bufoff) + ldsw + _i * 8192), 16, 0, 0); } while (0)
; #define PG8_LDA(dst, b, h) do { _Pragma("unroll") for (int m = 0; m < 4; ++m) _Pragma("unroll") for (int k = 0; k < 2; ++k) dst[m][k] = *(const LAS bf16x8*)(lds + PG8_SA(b, h) + aoff + m * 2048 + k * 1024); } while (0)
; #define PG8_LDB(dst, b, h) do { _Pragma("unroll") for (int n = 0; n < 2; ++n) _Pragma("unroll") for (int k = 0; k < 2; ++k) dst[n][k] = *(const LAS bf16x8*)(lds + PG8_SB(b, h) + boff + n * 2048 + k * 1024); } while (0)
; #define PG8_MMA(ai, bj, At, Bt) do { __builtin_amdgcn_s_setprio(1); _Pragma("unroll") for (int m = 0; m < 4; ++m) _Pragma("unroll") for (int n = 0; n < 2; ++n) _Pragma("unroll") for (int k = 0; k < 2; ++k) \
;         acc[ai][bj][m][n] = __builtin_amdgcn_mfma_f32_16x16x32_bf16(Bt[n][k], At[m][k], acc[ai][bj][m][n], 0, 0, 0); __builtin_amdgcn_s_setprio(0); } while (0)
; #define PG8_WAIT_V(n) asm volatile("s_waitcnt vmcnt(" #n ")" ::: "memory")
; #define PG8_WAIT_L(n) asm volatile("s_waitcnt lgkmcnt(" #n ")" ::: "memory")
; #define PG8_BAR __builtin_amdgcn_s_barrier()
; #define PG8_SCHED __builtin_amdgcn_sched_barrier(0)
; template <class Epi>
; __device__ __forceinline__ void gemm_phase(LAS unsigned char* lds, const Gemm g, const StaticOrder& S, const Epi& E, int wave_s) {
;     ...
;         for (int t = 0; t < nt; t += 2) {
;             const bool last = (t == nt - 2);
;             const char* a1 = cA + (size_t)(t + 1) * kstep;
;             const char* a2 = last ? nA : cA + (size_t)(t + 2) * kstep; const char* b2 = last ? nB : cB + (size_t)(t + 2) * kstep;
;             const char* a3 = a2 + kstep; const char* b3 = b2 + kstep;
;             PG8_LDB(B0, 0, 0); PG8_LDB(B1, 0, 1); PG8_SCHED; PG8_LDA(At, 0, 0); PG8_STAGE(PG8_SA(1, 1), a1 + hstepA, voffA);
;             PG8_WAIT_V(8); PG8_WAIT_L(0); PG8_BAR; PG8_MMA(0, 0, At, B0); PG8_MMA(0, 1, At, B1); PG8_BAR; PG8_SCHED;
;             PG8_LDA(At, 0, 1); PG8_STAGE(PG8_SB(0, 0), b2, voffB); PG8_STAGE(PG8_SB(0, 1), b2 + hstepB, voffB); PG8_STAGE(PG8_SA(0, 0), a2, voffA);
;             PG8_WAIT_V(8); PG8_WAIT_L(0); PG8_BAR; PG8_MMA(1, 0, At, B0); PG8_MMA(1, 1, At, B1); PG8_BAR; PG8_SCHED;
.LBB0_1188:
	s_add_u32 s6, s94, 0x100
	s_addc_u32 s7, s95, 0
	s_add_i32 s54, 0, 0x10000
	s_cmp_eq_u32 s51, 40
	s_cselect_b32 vcc_hi, s41, s7
	s_cselect_b32 vcc_lo, s40, s6
	s_cselect_b32 s9, s43, s50
	s_cselect_b32 s8, s42, s49
	s_add_i32 s70, 0, 0x14000
	v_add_u32_e32 v142, s54, v209
	v_add_u32_e32 v164, s70, v209
	ds_read_b128 v[130:133], v142
	ds_read_b128 v[134:137], v142 offset:1024
	ds_read_b128 v[138:141], v142 offset:2048
	ds_read_b128 v[142:145], v142 offset:3072
	ds_read_b128 v[186:189], v167
	ds_read_b128 v[190:193], v167 offset:1024
	ds_read_b128 v[194:197], v167 offset:2048
	ds_read_b128 v[198:201], v167 offset:3072
	ds_read_b128 v[210:213], v167 offset:4096
	ds_read_b128 v[214:217], v167 offset:5120
	ds_read_b128 v[232:235], v167 offset:6144
	ds_read_b128 v[174:177], v167 offset:7168
	ds_read_b128 v[146:149], v164
	ds_read_b128 v[170:173], v164 offset:1024
	ds_read_b128 v[178:181], v164 offset:2048
	ds_read_b128 v[182:185], v164 offset:3072
	v_lshl_add_u64 v[164:165], s[94:95], 0, v[160:161]
	s_add_i32 m0, s52, 0xc000
	global_load_lds_dwordx4 v[164:165], off
	v_lshl_add_u64 v[164:165], s[94:95], 0, v[162:163]
	s_add_i32 m0, s52, 0xe000
	s_nop 0
	global_load_lds_dwordx4 v[164:165], off
	s_waitcnt vmcnt(8)
	s_cmp_lg_u64 s[26:27], 0
	s_cbranch_scc1 .Lpp_lead_11
	s_waitcnt lgkmcnt(0)
.Lpp_lead_11:
	s_waitcnt lgkmcnt(4)
	s_barrier
	s_setprio 1
	s_waitcnt lgkmcnt(4)
	v_mfma_f32_16x16x32_bf16 v[78:81], v[130:133], v[186:189], v[78:81]
	v_mfma_f32_16x16x32_bf16 v[106:109], v[138:141], v[186:189], v[106:109]
	v_mfma_f32_16x16x32_bf16 v[74:77], v[130:133], v[194:197], v[74:77]
	v_mfma_f32_16x16x32_bf16 v[98:101], v[138:141], v[194:197], v[98:101]
	v_mfma_f32_16x16x32_bf16 v[70:73], v[130:133], v[210:213], v[70:73]
	v_mfma_f32_16x16x32_bf16 v[86:89], v[138:141], v[210:213], v[86:89]
	v_mfma_f32_16x16x32_bf16 v[62:65], v[130:133], v[232:235], v[62:65]
	v_mfma_f32_16x16x32_bf16 v[122:125], v[138:141], v[232:235], v[122:125]
	v_mfma_f32_16x16x32_bf16 v[78:81], v[134:137], v[190:193], v[78:81]
	v_mfma_f32_16x16x32_bf16 v[106:109], v[142:145], v[190:193], v[106:109]
	v_mfma_f32_16x16x32_bf16 v[74:77], v[134:137], v[198:201], v[74:77]
	v_mfma_f32_16x16x32_bf16 v[98:101], v[142:145], v[198:201], v[98:101]
	v_mfma_f32_16x16x32_bf16 v[70:73], v[134:137], v[214:217], v[70:73]
	v_mfma_f32_16x16x32_bf16 v[86:89], v[142:145], v[214:217], v[86:89]
	v_mfma_f32_16x16x32_bf16 v[62:65], v[134:137], v[174:177], v[62:65]
	v_mfma_f32_16x16x32_bf16 v[122:125], v[142:145], v[174:177], v[122:125]
	s_setprio 0
	s_setprio 1
	s_waitcnt lgkmcnt(0)
	v_mfma_f32_16x16x32_bf16 v[102:105], v[146:149], v[186:189], v[102:105]
	v_mfma_f32_16x16x32_bf16 v[34:37], v[178:181], v[186:189], v[34:37]
	v_mfma_f32_16x16x32_bf16 v[94:97], v[146:149], v[194:197], v[94:97]
	v_mfma_f32_16x16x32_bf16 v[30:33], v[178:181], v[194:197], v[30:33]
	v_mfma_f32_16x16x32_bf16 v[90:93], v[146:149], v[210:213], v[90:93]
	v_mfma_f32_16x16x32_bf16 v[26:29], v[178:181], v[210:213], v[26:29]
	v_mfma_f32_16x16x32_bf16 v[82:85], v[146:149], v[232:235], v[82:85]
	v_mfma_f32_16x16x32_bf16 v[22:25], v[178:181], v[232:235], v[22:25]
	v_mfma_f32_16x16x32_bf16 v[102:105], v[170:173], v[190:193], v[102:105]
	v_mfma_f32_16x16x32_bf16 v[34:37], v[182:185], v[190:193], v[34:37]
	v_mfma_f32_16x16x32_bf16 v[94:97], v[170:173], v[198:201], v[94:97]
	v_mfma_f32_16x16x32_bf16 v[30:33], v[182:185], v[198:201], v[30:33]
	v_mfma_f32_16x16x32_bf16 v[90:93], v[170:173], v[214:217], v[90:93]
	v_mfma_f32_16x16x32_bf16 v[26:29], v[182:185], v[214:217], v[26:29]
	v_mfma_f32_16x16x32_bf16 v[82:85], v[170:173], v[174:177], v[82:85]
	v_mfma_f32_16x16x32_bf16 v[22:25], v[182:185], v[174:177], v[22:25]
	s_setprio 0
	s_barrier
	s_add_i32 s54, s54, s65
	v_lshl_add_u64 v[164:165], s[8:9], 0, v[12:13]
	s_mov_b32 m0, s54
	ds_read_b128 v[174:177], v167 offset:16384
	ds_read_b128 v[186:189], v167 offset:17408
	ds_read_b128 v[190:193], v167 offset:18432
	ds_read_b128 v[194:197], v167 offset:19456
	ds_read_b128 v[198:201], v167 offset:20480
	ds_read_b128 v[210:213], v167 offset:21504
	ds_read_b128 v[214:217], v167 offset:22528
	ds_read_b128 v[232:235], v167 offset:23552
	global_load_lds_dwordx4 v[164:165], off
	s_add_i32 m0, s54, 0x2000
	s_add_u32 s58, s8, 0xb0000
	v_lshl_add_u64 v[202:203], s[8:9], 0, v[150:151]
	s_addc_u32 s59, s9, 0
	s_add_i32 s54, s70, s65
	global_load_lds_dwordx4 v[202:203], off
	v_lshl_add_u64 v[206:207], s[58:59], 0, v[12:13]
	s_mov_b32 m0, s54
	v_lshl_add_u64 v[218:219], vcc, 0, v[152:153]
	global_load_lds_dwordx4 v[206:207], off
	v_lshl_add_u64 v[206:207], s[58:59], 0, v[150:151]
	s_add_i32 m0, s54, 0x2000
	s_nop 0
	global_load_lds_dwordx4 v[206:207], off
	v_lshl_add_u64 v[206:207], vcc, 0, v[154:155]
	s_mov_b32 m0, s52
	s_nop 0
	global_load_lds_dwordx4 v[206:207], off
	s_mov_b32 m0, s53
	s_nop 0
	global_load_lds_dwordx4 v[218:219], off
	s_waitcnt vmcnt(8)
	s_waitcnt lgkmcnt(0)
	s_barrier
; #define PG8_STAGE(bufoff, gbase, voff) do { _Pragma("unroll") for (int _i = 0; _i < 2; ++_i) \
;         __builtin_amdgcn_global_load_lds((const unsigned*)((const char*)(gbase) + (voff)[_i]), (LAS unsigned*)(lds + (bufoff) + ldsw + _i * 8192), 16, 0, 0); } while (0)
; #define PG8_LDA(dst, b, h) do { _Pragma("unroll") for (int m = 0; m < 4; ++m) _Pragma("unroll") for (int k = 0; k < 2; ++k) dst[m][k] = *(const LAS bf16x8*)(lds + PG8_SA(b, h) + aoff + m * 2048 + k * 1024); } while (0)
; #define PG8_LDB(dst, b, h) do { _Pragma("unroll") for (int n = 0; n < 2; ++n) _Pragma("unroll") for (int k = 0; k < 2; ++k) dst[n][k] = *(const LAS bf16x8*)(lds + PG8_SB(b, h) + boff + n * 2048 + k * 1024); } while (0)
; #define PG8_MMA(ai, bj, At, Bt) do { __builtin_amdgcn_s_setprio(1); _Pragma("unroll") for (int m = 0; m < 4; ++m) _Pragma("unroll") for (int n = 0; n < 2; ++n) _Pragma("unroll") for (int k = 0; k < 2; ++k) \
;         acc[ai][bj][m][n] = __builtin_amdgcn_mfma_f32_16x16x32_bf16(Bt[n][k], At[m][k], acc[ai][bj][m][n], 0, 0, 0); __builtin_amdgcn_s_setprio(0); } while (0)
; #define PG8_WAIT_V(n) asm volatile("s_waitcnt vmcnt(" #n ")" ::: "memory")
; #define PG8_WAIT_L(n) asm volatile("s_waitcnt lgkmcnt(" #n ")" ::: "memory")
; #define PG8_BAR __builtin_amdgcn_s_barrier()
; #define PG8_SCHED __builtin_amdgcn_sched_barrier(0)
; template <class Epi>
; __device__ __forceinline__ void gemm_phase(LAS unsigned char* lds, const Gemm g, const StaticOrder& S, const Epi& E, int wave_s) {
;     ...
;             PG8_WAIT_V(8); PG8_WAIT_L(0); PG8_BAR; PG8_MMA(1, 0, At, B0); PG8_MMA(1, 1, At, B1); PG8_BAR; PG8_SCHED;
;             PG8_LDB(B0, 1, 0); PG8_LDB(B1, 1, 1); PG8_SCHED; PG8_LDA(At, 1, 0); PG8_STAGE(PG8_SA(0, 1), a2 + hstepA, voffA);
;             PG8_WAIT_V(8); PG8_WAIT_L(0); PG8_BAR; PG8_MMA(0, 0, At, B0); PG8_MMA(0, 1, At, B1); PG8_BAR; PG8_SCHED;
	s_setprio 1
	s_waitcnt lgkmcnt(0)
	v_mfma_f32_16x16x32_bf16 v[58:61], v[130:133], v[174:177], v[58:61]
	v_mfma_f32_16x16x32_bf16 v[118:121], v[138:141], v[174:177], v[118:121]
	v_mfma_f32_16x16x32_bf16 v[54:57], v[130:133], v[190:193], v[54:57]
	v_mfma_f32_16x16x32_bf16 v[126:129], v[138:141], v[190:193], v[126:129]
	v_mfma_f32_16x16x32_bf16 v[50:53], v[130:133], v[198:201], v[50:53]
	v_mfma_f32_16x16x32_bf16 v[114:117], v[138:141], v[198:201], v[114:117]
	v_mfma_f32_16x16x32_bf16 v[46:49], v[130:133], v[214:217], v[46:49]
	v_mfma_f32_16x16x32_bf16 v[110:113], v[138:141], v[214:217], v[110:113]
	v_mfma_f32_16x16x32_bf16 v[58:61], v[134:137], v[186:189], v[58:61]
	v_mfma_f32_16x16x32_bf16 v[118:121], v[142:145], v[186:189], v[118:121]
	v_mfma_f32_16x16x32_bf16 v[54:57], v[134:137], v[194:197], v[54:57]
	v_mfma_f32_16x16x32_bf16 v[126:129], v[142:145], v[194:197], v[126:129]
	v_mfma_f32_16x16x32_bf16 v[50:53], v[134:137], v[210:213], v[50:53]
	v_mfma_f32_16x16x32_bf16 v[114:117], v[142:145], v[210:213], v[114:117]
	v_mfma_f32_16x16x32_bf16 v[46:49], v[134:137], v[232:235], v[46:49]
	v_mfma_f32_16x16x32_bf16 v[110:113], v[142:145], v[232:235], v[110:113]
	s_setprio 0
	s_setprio 1
	v_mfma_f32_16x16x32_bf16 v[66:69], v[146:149], v[174:177], v[66:69]
	v_mfma_f32_16x16x32_bf16 v[14:17], v[178:181], v[174:177], v[14:17]
	v_mfma_f32_16x16x32_bf16 v[42:45], v[146:149], v[190:193], v[42:45]
	v_mfma_f32_16x16x32_bf16 v[8:11], v[178:181], v[190:193], v[8:11]
	v_mfma_f32_16x16x32_bf16 v[38:41], v[146:149], v[198:201], v[38:41]
	v_mfma_f32_16x16x32_bf16 v[4:7], v[178:181], v[198:201], v[4:7]
	v_mfma_f32_16x16x32_bf16 v[18:21], v[146:149], v[214:217], v[18:21]
	v_mfma_f32_16x16x32_bf16 v[0:3], v[178:181], v[214:217], v[0:3]
	v_mfma_f32_16x16x32_bf16 v[66:69], v[170:173], v[186:189], v[66:69]
	v_mfma_f32_16x16x32_bf16 v[14:17], v[182:185], v[186:189], v[14:17]
	v_mfma_f32_16x16x32_bf16 v[42:45], v[170:173], v[194:197], v[42:45]
	v_mfma_f32_16x16x32_bf16 v[8:11], v[182:185], v[194:197], v[8:11]
	v_mfma_f32_16x16x32_bf16 v[38:41], v[170:173], v[210:213], v[38:41]
	v_mfma_f32_16x16x32_bf16 v[4:7], v[182:185], v[210:213], v[4:7]
	v_mfma_f32_16x16x32_bf16 v[18:21], v[170:173], v[232:235], v[18:21]
	v_mfma_f32_16x16x32_bf16 v[0:3], v[182:185], v[232:235], v[0:3]
	s_setprio 0
	s_barrier
	s_add_i32 s54, 0, 0x18000
	s_add_i32 s70, 0, 0x1c000
	v_add_u32_e32 v142, s54, v209
	v_add_u32_e32 v169, s70, v209
	ds_read_b128 v[130:133], v142
	ds_read_b128 v[134:137], v142 offset:1024
	ds_read_b128 v[138:141], v142 offset:2048
	ds_read_b128 v[142:145], v142 offset:3072
	ds_read_b128 v[182:185], v167 offset:32768
	ds_read_b128 v[186:189], v167 offset:33792
	ds_read_b128 v[190:193], v167 offset:34816
	ds_read_b128 v[194:197], v167 offset:35840
	ds_read_b128 v[198:201], v167 offset:36864
	ds_read_b128 v[210:213], v167 offset:37888
	ds_read_b128 v[214:217], v167 offset:38912
	ds_read_b128 v[232:235], v167 offset:39936
	ds_read_b128 v[146:149], v169
	ds_read_b128 v[170:173], v169 offset:1024
	ds_read_b128 v[174:177], v169 offset:2048
	ds_read_b128 v[178:181], v169 offset:3072
	s_add_u32 s58, vcc_lo, 0xb0000
	s_addc_u32 s59, vcc_hi, 0
	s_mov_b32 m0, s35
	v_lshl_add_u64 v[224:225], s[58:59], 0, v[154:155]
	global_load_lds_dwordx4 v[224:225], off
	v_lshl_add_u64 v[224:225], s[58:59], 0, v[152:153]
	s_mov_b32 m0, s18
	s_nop 0
	global_load_lds_dwordx4 v[224:225], off
	s_waitcnt vmcnt(8)
	s_cmp_lg_u64 s[26:27], 0
	s_cbranch_scc1 .Lpp_lead_12
	s_waitcnt lgkmcnt(0)
; #define PG8_STAGE(bufoff, gbase, voff) do { _Pragma("unroll") for (int _i = 0; _i < 2; ++_i) \
;         __builtin_amdgcn_global_load_lds((const unsigned*)((const char*)(gbase) + (voff)[_i]), (LAS unsigned*)(lds + (bufoff) + ldsw + _i * 8192), 16, 0, 0); } while (0)
; #define PG8_LDA(dst, b, h) do { _Pragma("unroll") for (int m = 0; m < 4; ++m) _Pragma("unroll") for (int k = 0; k < 2; ++k) dst[m][k] = *(const LAS bf16x8*)(lds + PG8_SA(b, h) + aoff + m * 2048 + k * 1024); } while (0)
; #define PG8_MMA(ai, bj, At, Bt) do { __builtin_amdgcn_s_setprio(1); _Pragma("unroll") for (int m = 0; m < 4; ++m) _Pragma("unroll") for (int n = 0; n < 2; ++n) _Pragma("unroll") for (int k = 0; k < 2; ++k) \
;         acc[ai][bj][m][n] = __builtin_amdgcn_mfma_f32_16x16x32_bf16(Bt[n][k], At[m][k], acc[ai][bj][m][n], 0, 0, 0); __builtin_amdgcn_s_setprio(0); } while (0)
; #define PG8_WAIT_V(n) asm volatile("s_waitcnt vmcnt(" #n ")" ::: "memory")
; #define PG8_WAIT_L(n) asm volatile("s_waitcnt lgkmcnt(" #n ")" ::: "memory")
; #define PG8_BAR __builtin_amdgcn_s_barrier()
; #define PG8_SCHED __builtin_amdgcn_sched_barrier(0)
; template <class Epi>
; __device__ __forceinline__ void gemm_phase(LAS unsigned char* lds, const Gemm g, const StaticOrder& S, const Epi& E, int wave_s) {
;     ...
;             PG8_WAIT_V(8); PG8_WAIT_L(0); PG8_BAR; PG8_MMA(0, 0, At, B0); PG8_MMA(0, 1, At, B1); PG8_BAR; PG8_SCHED;
;             PG8_LDA(At, 1, 1); PG8_STAGE(PG8_SB(1, 0), b3, voffB); PG8_STAGE(PG8_SB(1, 1), b3 + hstepB, voffB); PG8_STAGE(PG8_SA(1, 0), a3, voffA);
;             PG8_WAIT_V(8); PG8_WAIT_L(0); PG8_BAR; PG8_MMA(1, 0, At, B0); PG8_MMA(1, 1, At, B1); PG8_BAR; PG8_SCHED;
;         }
;         if (wr == 0) PG8_BAR;
.Lpp_lead_12:
	s_waitcnt lgkmcnt(4)
	s_barrier
	s_setprio 1
	s_waitcnt lgkmcnt(4)
	v_mfma_f32_16x16x32_bf16 v[78:81], v[130:133], v[182:185], v[78:81]
	v_mfma_f32_16x16x32_bf16 v[106:109], v[138:141], v[182:185], v[106:109]
	v_mfma_f32_16x16x32_bf16 v[74:77], v[130:133], v[190:193], v[74:77]
	v_mfma_f32_16x16x32_bf16 v[98:101], v[138:141], v[190:193], v[98:101]
	v_mfma_f32_16x16x32_bf16 v[70:73], v[130:133], v[198:201], v[70:73]
	v_mfma_f32_16x16x32_bf16 v[86:89], v[138:141], v[198:201], v[86:89]
	v_mfma_f32_16x16x32_bf16 v[62:65], v[130:133], v[214:217], v[62:65]
	v_mfma_f32_16x16x32_bf16 v[122:125], v[138:141], v[214:217], v[122:125]
	v_mfma_f32_16x16x32_bf16 v[78:81], v[134:137], v[186:189], v[78:81]
	v_mfma_f32_16x16x32_bf16 v[106:109], v[142:145], v[186:189], v[106:109]
	v_mfma_f32_16x16x32_bf16 v[74:77], v[134:137], v[194:197], v[74:77]
	v_mfma_f32_16x16x32_bf16 v[98:101], v[142:145], v[194:197], v[98:101]
	v_mfma_f32_16x16x32_bf16 v[70:73], v[134:137], v[210:213], v[70:73]
	v_mfma_f32_16x16x32_bf16 v[86:89], v[142:145], v[210:213], v[86:89]
	v_mfma_f32_16x16x32_bf16 v[62:65], v[134:137], v[232:235], v[62:65]
	v_mfma_f32_16x16x32_bf16 v[122:125], v[142:145], v[232:235], v[122:125]
	s_setprio 0
	s_setprio 1
	s_waitcnt lgkmcnt(0)
	v_mfma_f32_16x16x32_bf16 v[102:105], v[146:149], v[182:185], v[102:105]
	v_mfma_f32_16x16x32_bf16 v[34:37], v[174:177], v[182:185], v[34:37]
	v_mfma_f32_16x16x32_bf16 v[94:97], v[146:149], v[190:193], v[94:97]
	v_mfma_f32_16x16x32_bf16 v[30:33], v[174:177], v[190:193], v[30:33]
	v_mfma_f32_16x16x32_bf16 v[90:93], v[146:149], v[198:201], v[90:93]
	v_mfma_f32_16x16x32_bf16 v[26:29], v[174:177], v[198:201], v[26:29]
	v_mfma_f32_16x16x32_bf16 v[82:85], v[146:149], v[214:217], v[82:85]
	v_mfma_f32_16x16x32_bf16 v[22:25], v[174:177], v[214:217], v[22:25]
	v_mfma_f32_16x16x32_bf16 v[102:105], v[170:173], v[186:189], v[102:105]
	v_mfma_f32_16x16x32_bf16 v[34:37], v[178:181], v[186:189], v[34:37]
	v_mfma_f32_16x16x32_bf16 v[94:97], v[170:173], v[194:197], v[94:97]
	v_mfma_f32_16x16x32_bf16 v[30:33], v[178:181], v[194:197], v[30:33]
	v_mfma_f32_16x16x32_bf16 v[90:93], v[170:173], v[210:213], v[90:93]
	v_mfma_f32_16x16x32_bf16 v[26:29], v[178:181], v[210:213], v[26:29]
	v_mfma_f32_16x16x32_bf16 v[82:85], v[170:173], v[232:235], v[82:85]
	v_mfma_f32_16x16x32_bf16 v[22:25], v[178:181], v[232:235], v[22:25]
	s_setprio 0
	s_barrier
	s_add_i32 s54, s54, s65
	v_lshl_add_u64 v[164:165], v[164:165], 0, s[84:85]
	s_mov_b32 m0, s54
	ds_read_b128 v[182:185], v167 offset:49152
	ds_read_b128 v[186:189], v167 offset:50176
	ds_read_b128 v[190:193], v167 offset:51200
	ds_read_b128 v[194:197], v167 offset:52224
	ds_read_b128 v[198:201], v167 offset:53248
	ds_read_b128 v[210:213], v167 offset:54272
	ds_read_b128 v[214:217], v167 offset:55296
	ds_read_b128 v[232:235], v167 offset:56320
	global_load_lds_dwordx4 v[164:165], off
	s_add_i32 m0, s54, 0x2000
	s_add_u32 s8, s8, 0xb0080
	v_lshl_add_u64 v[164:165], v[202:203], 0, s[84:85]
	s_addc_u32 s9, s9, 0
	s_add_i32 s54, s70, s65
	global_load_lds_dwordx4 v[164:165], off
	v_lshl_add_u64 v[164:165], s[8:9], 0, v[12:13]
	s_mov_b32 m0, s54
	s_nop 0
	global_load_lds_dwordx4 v[164:165], off
	v_lshl_add_u64 v[164:165], s[8:9], 0, v[150:151]
	s_add_i32 m0, s54, 0x2000
	s_nop 0
	global_load_lds_dwordx4 v[164:165], off
	v_lshl_add_u64 v[164:165], v[206:207], 0, s[84:85]
	s_mov_b32 m0, s45
	s_nop 0
	global_load_lds_dwordx4 v[164:165], off
	v_lshl_add_u64 v[164:165], v[218:219], 0, s[84:85]
	s_mov_b32 m0, s46
	s_nop 0
	global_load_lds_dwordx4 v[164:165], off
	s_waitcnt vmcnt(8)
	s_waitcnt lgkmcnt(0)
	s_barrier
	s_setprio 1
	s_waitcnt lgkmcnt(0)
	v_mfma_f32_16x16x32_bf16 v[58:61], v[130:133], v[182:185], v[58:61]
	v_mfma_f32_16x16x32_bf16 v[118:121], v[138:141], v[182:185], v[118:121]
	v_mfma_f32_16x16x32_bf16 v[54:57], v[130:133], v[190:193], v[54:57]
	v_mfma_f32_16x16x32_bf16 v[126:129], v[138:141], v[190:193], v[126:129]
	v_mfma_f32_16x16x32_bf16 v[50:53], v[130:133], v[198:201], v[50:53]
	v_mfma_f32_16x16x32_bf16 v[114:117], v[138:141], v[198:201], v[114:117]
	v_mfma_f32_16x16x32_bf16 v[46:49], v[130:133], v[214:217], v[46:49]
	v_mfma_f32_16x16x32_bf16 v[110:113], v[138:141], v[214:217], v[110:113]
	v_mfma_f32_16x16x32_bf16 v[58:61], v[134:137], v[186:189], v[58:61]
	v_mfma_f32_16x16x32_bf16 v[118:121], v[142:145], v[186:189], v[118:121]
	v_mfma_f32_16x16x32_bf16 v[54:57], v[134:137], v[194:197], v[54:57]
	v_mfma_f32_16x16x32_bf16 v[126:129], v[142:145], v[194:197], v[126:129]
	v_mfma_f32_16x16x32_bf16 v[50:53], v[134:137], v[210:213], v[50:53]
	v_mfma_f32_16x16x32_bf16 v[114:117], v[142:145], v[210:213], v[114:117]
	v_mfma_f32_16x16x32_bf16 v[46:49], v[134:137], v[232:235], v[46:49]
	v_mfma_f32_16x16x32_bf16 v[110:113], v[142:145], v[232:235], v[110:113]
	s_setprio 0
	s_setprio 1
	v_mfma_f32_16x16x32_bf16 v[66:69], v[146:149], v[182:185], v[66:69]
	v_mfma_f32_16x16x32_bf16 v[14:17], v[174:177], v[182:185], v[14:17]
	v_mfma_f32_16x16x32_bf16 v[42:45], v[146:149], v[190:193], v[42:45]
	v_mfma_f32_16x16x32_bf16 v[8:11], v[174:177], v[190:193], v[8:11]
	v_mfma_f32_16x16x32_bf16 v[38:41], v[146:149], v[198:201], v[38:41]
	v_mfma_f32_16x16x32_bf16 v[4:7], v[174:177], v[198:201], v[4:7]
	v_mfma_f32_16x16x32_bf16 v[18:21], v[146:149], v[214:217], v[18:21]
	v_mfma_f32_16x16x32_bf16 v[0:3], v[174:177], v[214:217], v[0:3]
	v_mfma_f32_16x16x32_bf16 v[66:69], v[170:173], v[186:189], v[66:69]
	v_mfma_f32_16x16x32_bf16 v[14:17], v[178:181], v[186:189], v[14:17]
	v_mfma_f32_16x16x32_bf16 v[42:45], v[170:173], v[194:197], v[42:45]
	v_mfma_f32_16x16x32_bf16 v[8:11], v[178:181], v[194:197], v[8:11]
	v_mfma_f32_16x16x32_bf16 v[38:41], v[170:173], v[210:213], v[38:41]
	v_mfma_f32_16x16x32_bf16 v[4:7], v[178:181], v[210:213], v[4:7]
	v_mfma_f32_16x16x32_bf16 v[18:21], v[170:173], v[232:235], v[18:21]
	v_mfma_f32_16x16x32_bf16 v[0:3], v[178:181], v[232:235], v[0:3]
	s_setprio 0
	s_barrier
	s_add_i32 s51, s51, 2
	s_add_u32 s49, s49, 0x100
	s_addc_u32 s50, s50, 0
	s_cmp_gt_u32 s51, 41
	s_mov_b64 s[94:95], s[6:7]
	s_cbranch_scc0 .LBB0_1188
	s_and_b64 vcc, exec, s[26:27]
	s_cbranch_vccz .LBB0_1191
	s_barrier
